# blocked stage-image copy of W1T as P1 big-GEMM B operand (contiguous KiB LDS-DMA pieces)
# baseline (speedup 1.0000x reference)
; #define LAS __attribute__((address_space(3)))
; #define LDS_WAIT() asm volatile("s_waitcnt lgkmcnt(0)" ::: "memory")
; __device__ __forceinline__ unsigned pk2(float lo, float hi) { f32x2_t v = {lo, hi}; bf16x2_t b = __builtin_convertvector(v, bf16x2_t); return __builtin_bit_cast(unsigned, b); }
; __device__ __forceinline__ void p0_item(const float* W, int N, int scol0, int nvalid, const float* gain, int gmask, bf16* WT, int ldk, int koff, int drow0, int k0, LAS float* scr, int lane) {
;     const bool al16 = ((scol0 & 3) == 0) && ((N & 3) == 0) && nvalid == 32;
;     if (al16) {
;         f32x4 v[8];
; #pragma unroll
;         for (int i = 0; i < 8; ++i) { const int p_ = lane + 64 * i; v[i] = __builtin_nontemporal_load((const f32x4*)(W + (size_t)(k0 + (p_ >> 3)) * N + scol0 + (p_ & 7) * 4)); }
; #pragma unroll
;         for (int i = 0; i < 8; ++i) { const int p_ = lane + 64 * i, kk = p_ >> 3, c = (p_ & 7) * 4; const float g = gain ? gain[(k0 + kk) & gmask] : 1.0f;
;             scr[kk * 33 + c] = v[i][0] * g; scr[kk * 33 + c + 1] = v[i][1] * g; scr[kk * 33 + c + 2] = v[i][2] * g; scr[kk * 33 + c + 3] = v[i][3] * g; }
;     } else {
;         float v[32];
; #pragma unroll
;         for (int i = 0; i < 32; ++i) { const int kk = 2 * i + (lane >> 5), c = lane & 31; v[i] = 0.f; if (c < nvalid) v[i] = W[(size_t)(k0 + kk) * N + scol0 + c]; }
; #pragma unroll
;         for (int i = 0; i < 32; ++i) { const int kk = 2 * i + (lane >> 5), c = lane & 31; scr[kk * 33 + c] = (gain && c < nvalid) ? v[i] * gain[(k0 + kk) & gmask] : v[i]; }
;     }
;     LDS_WAIT(); asm volatile("" ::: "memory");
;     const int c8 = lane & 7;
; #pragma unroll
;     for (int j = 0; j < 4; ++j) { const int n = (lane >> 3) + 8 * j; const LAS float* s = scr + (8 * c8) * 33 + n;
;         v4u o; o.x = pk2(s[0 * 33], s[1 * 33]); o.y = pk2(s[2 * 33], s[3 * 33]); o.z = pk2(s[4 * 33], s[5 * 33]); o.w = pk2(s[6 * 33], s[7 * 33]);
;         *(v4u*)(WT + (size_t)(drow0 + n) * ldk + koff + k0 + 8 * c8) = o; }
;     LDS_WAIT(); asm volatile("" ::: "memory");
; }
; __device__ __forceinline__ void p0_prologue(const Args& a, Frame& F) {
;     LAS float* scr = (LAS float*)(F.lds + F.wave * 16384);
;     const int gw = F.vcu * NWAVES + F.wave, NGW = F.G * NWAVES;
;     unsigned char* ws = a.ws;
;     for (int it = gw; it < P0_NEARLY; it += NGW) p0_weight_item(a, it, scr, F.lane);
.LBB0_8:
	s_ashr_i32 s3, s0, 6
	s_lshl_b32 s33, s11, 3
	v_and_b32_e32 v1, 63, v95
	s_add_i32 s0, s33, s3
	s_lshl_b32 s10, s1, 3
	s_cmpk_gt_i32 s0, 0x197f
	v_lshlrev_b32_e32 v82, 4, v1
	v_lshlrev_b32_e32 v94, 3, v1
	s_cbranch_scc1 .LBB0_163
	v_lshrrev_b32_e32 v52, 5, v1
	s_movk_i32 s5, 0x84
	v_mov_b32_e32 v2, 0x210
	v_mad_u32_u24 v6, v52, s5, v2
	v_mov_b32_e32 v2, 0x420
	s_lshl_b32 s4, s3, 14
	v_and_b32_e32 v51, 31, v95
	v_mad_u32_u24 v7, v52, s5, v2
	v_mov_b32_e32 v2, 0x630
	v_lshrrev_b32_e32 v53, 3, v1
	v_lshrrev_b32_e32 v120, 2, v53
	v_lshlrev_b32_e32 v120, 11, v120
	v_and_b32_e32 v121, 3, v53
	v_lshl_add_u32 v120, v121, 6, v120
	v_and_b32_e32 v121, 7, v1
	v_lshrrev_b32_e32 v122, 2, v121
	v_lshl_add_u32 v120, v122, 10, v120
	v_and_b32_e32 v121, 3, v121
	v_lshl_add_u32 v120, v121, 4, v120
	v_xor_b32_e32 v121, 32, v120
	v_and_b32_e32 v10, 56, v94
	s_add_i32 s4, s4, 0
	v_lshlrev_b32_e32 v34, 2, v51
	v_mad_u32_u24 v8, v52, s5, v2
	v_mov_b32_e32 v2, 0x840
	v_mul_u32_u24_e32 v3, 0x84, v10
	v_lshlrev_b32_e32 v11, 2, v53
	v_mov_b32_e32 v35, 0
	v_add_u32_e32 v4, s4, v34
	v_mad_u32_u24 v9, v52, s5, v2
	v_and_b32_e32 v2, 0x70, v82
	v_add3_u32 v63, s4, v3, v11
	v_lshl_add_u64 v[36:37], s[58:59], 0, v[34:35]
	v_mov_b32_e32 v3, v35
	v_lshlrev_b32_e32 v34, 1, v10
	v_add_u32_e32 v61, s4, v2
	v_lshl_add_u64 v[38:39], s[58:59], 0, v[2:3]
	v_lshl_add_u64 v[40:41], s[54:55], 0, v[2:3]
	v_lshl_add_u64 v[42:43], s[52:53], 0, v[2:3]
	v_lshl_add_u64 v[2:3], s[96:97], 0, v[34:35]
	s_mov_b64 s[4:5], 0x1180000
	s_cmp_lg_u64 s[56:57], 0
	v_lshl_add_u64 v[44:45], v[2:3], 0, s[4:5]
	s_mov_b64 s[4:5], 0xc00000
	v_mul_u32_u24_e32 v5, 0x84, v52
	s_cselect_b64 s[8:9], -1, 0
	v_lshl_add_u64 v[46:47], v[2:3], 0, s[4:5]
	s_cmp_lg_u64 s[50:51], 0
	s_mov_b64 s[4:5], 0x100000
	s_mov_b32 s7, 0
	v_or_b32_e32 v54, 8, v53
	v_or_b32_e32 v55, 16, v53
	v_or_b32_e32 v56, 24, v53
	v_or_b32_e32 v57, 32, v53
	v_or_b32_e32 v58, 40, v53
	v_or_b32_e32 v59, 48, v53
	v_or_b32_e32 v60, 56, v53
	v_mul_u32_u24_e32 v62, 0x84, v53
	s_cselect_b64 s[12:13], -1, 0
	v_lshl_add_u64 v[48:49], v[2:3], 0, s[4:5]
	s_lshl_b32 s16, s0, 5
	s_lshl_b32 s17, s10, 5
	s_lshl_b32 s18, s0, 4
	s_lshl_b32 s19, s10, 4
	s_lshl_b32 s20, s0, 1
	s_lshl_b32 s21, s10, 1
	v_add_u32_e32 v64, v4, v6
	v_add_u32_e32 v65, v4, v8
	s_movk_i32 s22, 0x5800
	v_add_u32_e32 v66, v4, v5
	v_add_u32_e32 v67, v4, v7
	v_add_u32_e32 v68, v4, v9
	s_mov_b32 s23, s0
	s_branch .LBB0_12
.LBB0_10:
	v_add_u32_e32 v10, 0x18c0, v71
	ds_write2_b32 v10, v6, v7 offset1:1
	v_add_u32_e32 v6, 0x18c8, v71
	ds_write2_b32 v6, v8, v9 offset1:1
	s_waitcnt vmcnt(0)
	v_pk_mul_f32 v[2:3], v[2:3], v[18:19] op_sel_hi:[1,0]
	v_add_u32_e32 v6, 0x1ce0, v71
	ds_write2_b32 v6, v2, v3 offset1:1
	v_pk_mul_f32 v[2:3], v[4:5], v[18:19] op_sel_hi:[1,0]
	v_add_u32_e32 v4, 0x1ce8, v71
	ds_write2_b32 v4, v2, v3 offset1:1
	s_waitcnt lgkmcnt(0)
	ds_read2_b32 v[6:7], v63 offset0:33 offset1:41
	ds_read2_b32 v[8:9], v63 offset1:8
	ds_read2_b32 v[10:11], v63 offset0:66 offset1:74
	ds_read2_b32 v[12:13], v63 offset0:99 offset1:107
	ds_read2_b32 v[14:15], v63 offset0:132 offset1:140
	ds_read2_b32 v[16:17], v63 offset0:165 offset1:173
	ds_read2_b32 v[18:19], v63 offset0:198 offset1:206
	ds_read2_b32 v[20:21], v63 offset0:231 offset1:239
	s_mul_i32 s4, s6, 0xffffea00
	s_add_i32 s4, s4, s16
	s_lshr_b32 s98, s4, 5
	s_lshr_b32 s99, s98, 3
	s_lshl_b32 s99, s99, 19
	s_lshl_b32 s100, s6, 15
	s_add_u32 s99, s99, s100
	s_bfe_u32 s100, s98, 0x10002
	s_lshl_b32 s100, s100, 14
	s_add_u32 s99, s99, s100
	s_and_b32 s100, s98, 3
	s_lshl_b32 s100, s100, 12
	s_add_u32 s99, s99, s100
	s_add_u32 s100, s96, 0x17ec0000
	s_addc_u32 s101, s97, 0
	s_add_u32 s100, s100, s99
	s_addc_u32 s101, s101, 0
	v_add_u32_e32 v24, s4, v53
	s_ashr_i32 s15, s14, 31
	v_ashrrev_i32_e32 v25, 31, v24
	v_lshl_add_u64 v[22:23], s[14:15], 1, v[48:49]
	v_lshlrev_b64 v[26:27], 11, v[24:25]
	s_waitcnt lgkmcnt(6)
	v_cvt_pk_bf16_f32 v2, v8, v6
	s_waitcnt lgkmcnt(4)
	v_cvt_pk_bf16_f32 v3, v10, v12
	s_waitcnt lgkmcnt(2)
	v_cvt_pk_bf16_f32 v4, v14, v16
	s_waitcnt lgkmcnt(0)
	v_cvt_pk_bf16_f32 v5, v18, v20
	v_lshl_add_u64 v[26:27], v[22:23], 0, v[26:27]
	v_add_u32_e32 v6, 8, v24
	global_store_dwordx4 v[26:27], v[2:5], off
	global_store_dwordx4 v120, v[2:5], s[100:101]
	s_nop 1
	v_cvt_pk_bf16_f32 v2, v9, v7
	v_ashrrev_i32_e32 v7, 31, v6
	v_cvt_pk_bf16_f32 v3, v11, v13
	v_cvt_pk_bf16_f32 v4, v15, v17
	v_cvt_pk_bf16_f32 v5, v19, v21
	v_lshlrev_b64 v[6:7], 11, v[6:7]
	ds_read2_b32 v[8:9], v63 offset0:49 offset1:57
	ds_read2_b32 v[10:11], v63 offset0:16 offset1:24
	ds_read2_b32 v[12:13], v63 offset0:82 offset1:90
	ds_read2_b32 v[14:15], v63 offset0:115 offset1:123
	ds_read2_b32 v[16:17], v63 offset0:148 offset1:156
	ds_read2_b32 v[18:19], v63 offset0:181 offset1:189
	ds_read2_b32 v[20:21], v63 offset0:214 offset1:222
	ds_read2_b32 v[26:27], v63 offset0:247 offset1:255
	v_lshl_add_u64 v[6:7], v[22:23], 0, v[6:7]
	global_store_dwordx4 v[6:7], v[2:5], off
	global_store_dwordx4 v120, v[2:5], s[100:101] offset:256
	v_add_u32_e32 v6, 16, v24
	v_ashrrev_i32_e32 v7, 31, v6
	v_lshlrev_b64 v[6:7], 11, v[6:7]
	s_waitcnt lgkmcnt(6)
	v_cvt_pk_bf16_f32 v2, v10, v8
	s_waitcnt lgkmcnt(4)
	v_cvt_pk_bf16_f32 v3, v12, v14
	s_waitcnt lgkmcnt(2)
	v_cvt_pk_bf16_f32 v4, v16, v18
	s_waitcnt lgkmcnt(0)
	v_cvt_pk_bf16_f32 v5, v20, v26
	v_lshl_add_u64 v[6:7], v[22:23], 0, v[6:7]
	global_store_dwordx4 v[6:7], v[2:5], off
	global_store_dwordx4 v121, v[2:5], s[100:101] offset:512
	v_add_u32_e32 v6, 24, v24
	v_ashrrev_i32_e32 v7, 31, v6
	v_lshlrev_b64 v[6:7], 11, v[6:7]
	v_cvt_pk_bf16_f32 v2, v11, v9
	v_cvt_pk_bf16_f32 v3, v13, v15
	v_cvt_pk_bf16_f32 v4, v17, v19
	v_cvt_pk_bf16_f32 v5, v21, v27
	v_lshl_add_u64 v[6:7], v[22:23], 0, v[6:7]
	global_store_dwordx4 v[6:7], v[2:5], off
	global_store_dwordx4 v121, v[2:5], s[100:101] offset:768
	s_waitcnt lgkmcnt(0)

; #define PG8_LAS __attribute__((address_space(3)))
; #define S xcd_barrier(bar);
; template <class Epi, bool ALIGN_EPI, bool ABLK = false>
; __device__ __forceinline__ void gemm_phase(PG8_LAS unsigned char* lds, const Gemm g, const StaticOrder& S, const Epi& E) {
;     const int tid = threadIdx.x, wid = __builtin_amdgcn_readfirstlane(tid >> 6), lane = tid & 63, wr = wid >> 2, wc = wid & 3, fr = lane & 15, fq = lane >> 4;
;     const int K = g.K, nt = K / BK;
;     unsigned voffA[2], voffB[2];
; #pragma unroll
;     for (int i = 0; i < 2; ++i) { int R, C; stage_rc(tid * 16 + i * 8192, R, C); const int Rb = Epi::PERM ? ((R & ~31) + perm32(R & 31)) : R;
;         voffA[i] = ABLK ? (unsigned)(tid * 16 + i * 8192) : (unsigned)(R * g.lda + C) * 2u; voffB[i] = (unsigned)(Rb * g.ldb + C) * 2u; }
;     const size_t kstepB = (size_t)(BK * 2), kstepA = ABLK ? (size_t)(2 * HTB) : (size_t)(BK * 2);
;     const size_t hstepA = ABLK ? (size_t)HTB : (size_t)HALF * g.lda * 2, hstepB = (size_t)HALF * g.ldb * 2;
;     const size_t tstepA = ABLK ? (size_t)(g.K / BK) * (2 * HTB) : 2 * hstepA, tstepB = 2 * hstepB;
;     const unsigned ldsw = (unsigned)wid * 1024u;
;     const int aoff = lds_byte(wr * 64 + fr, fq * 8), boff = lds_byte(wc * 32 + fr, fq * 8);
;     ...
;     Unit cur, nxt; int ui = 0;
;     if (!S.next(0, cur)) return;
;     Acc acc;
; #pragma unroll
;     for (int a = 0; a < 2; ++a)
; #pragma unroll
;         for (int b = 0; b < 2; ++b)
; #pragma unroll
;             for (int m = 0; m < 4; ++m)
; #pragma unroll
;                 for (int n = 0; n < 2; ++n) acc[a][b][m][n] = (f32x4){0.f, 0.f, 0.f, 0.f};
;     bf16x8 At[4][2], B0[2][2], B1[2][2];
;     const char* cA = PG8_ABASE(cur); const char* cB = PG8_BBASE(cur);
;     constexpr int RS_MAXT = 12;
;     PG8_LAS float* RS = (PG8_LAS float*)(lds + EX_OFF);
;     f32x4 rq[RS_MAXT][2];
;     if constexpr (Epi::RSTD_LDS) {
; #pragma unroll
;         for (int i = 0; i < RS_MAXT; ++i) { Unit t; if (S.next(i, t)) { const float* p = E.ssqp + (size_t)(t.pm * BM + wid * 32 + (lane & 31)) * 16 + (lane >> 5) * 8; rq[i][0] = *(const f32x4*)p; rq[i][1] = *(const f32x4*)(p + 4); } }
;     }
;     PG8_STAGE(PG8_SB(0, 0), cB, voffB); PG8_STAGE(PG8_SB(0, 1), cB + hstepB, voffB); PG8_STAGE(PG8_SA(0, 0), cA, voffA); PG8_STAGE(PG8_SA(0, 1), cA + hstepA, voffA);
;     if constexpr (Epi::RSTD_LDS) {
.LBB0_348:
	v_lshlrev_b32_e32 v101, 1, v99
	v_lshrrev_b32_e32 v102, 5, v0
	s_ashr_i32 s9, s8, 31
	s_ashr_i32 s11, s10, 31
	v_and_b32_e32 v101, 24, v101
	v_and_b32_e32 v102, 4, v102
	v_and_b32_e32 v103, 3, v99
	s_lshl_b64 s[4:5], s[8:9], 19
	s_lshl_b64 s[22:23], s[10:11], 19
	v_or3_b32 v101, v102, v103, v101
	v_lshrrev_b32_e32 v102, 3, v0
	s_add_u32 s100, s96, 0x17ec0000
	s_addc_u32 s101, s97, 0
	s_add_u32 s22, s100, s22
	v_and_or_b32 v103, v102, 32, v101
	v_or_b32_e32 v102, 64, v102
	s_movk_i32 s9, 0x60
	s_addc_u32 s23, s101, s23
	v_and_or_b32 v101, v102, s9, v101
	s_lshl_b32 s9, s30, 10
	s_add_u32 s11, s96, 0x3c40000
	v_lshlrev_b32_e32 v146, 4, v0
	s_addc_u32 s54, s97, 0
	v_bitop3_b32 v100, v146, v98, 48 bitop3:0x6c
	s_add_u32 s24, s11, s4
	v_and_or_b32 v100, v0, 64, v100
	s_addc_u32 s25, s54, s5
	s_add_i32 s55, s9, 0
	v_mov_b32_e32 v148, v146
	s_add_i32 m0, s55, 0x10000
	v_add_u32_e32 v150, 0x2000, v146
	global_load_lds_dwordx4 v148, s[22:23]
	s_add_i32 m0, s55, 0x12000
	s_add_u32 s4, s22, 0x4000
	global_load_lds_dwordx4 v150, s[22:23]
	s_addc_u32 s5, s23, 0
	s_add_i32 m0, s55, 0x14000
	v_mov_b32_e32 v147, 0
	global_load_lds_dwordx4 v148, s[4:5]
	s_add_i32 m0, s55, 0x16000
	v_lshl_add_u64 v[100:101], s[24:25], 0, v[146:147]
	global_load_lds_dwordx4 v150, s[4:5]
	s_mov_b32 m0, s55
	s_mov_b64 s[4:5], 0x2000
	s_add_i32 s56, s55, 0x2000
	global_load_lds_dwordx4 v146, s[24:25]
	v_lshl_add_u64 v[102:103], v[100:101], 0, s[4:5]
	s_mov_b32 m0, s56
	s_add_i32 s57, s55, 0x4000
	s_mov_b64 s[4:5], 0x4000
	global_load_lds_dwordx4 v[102:103], off
	v_lshl_add_u64 v[102:103], v[100:101], 0, s[4:5]
	s_mov_b32 m0, s57
	s_mov_b64 s[4:5], 0x6000
	s_add_i32 s58, s55, 0x6000
	global_load_lds_dwordx4 v[102:103], off
	v_lshl_add_u64 v[102:103], v[100:101], 0, s[4:5]
	s_mov_b32 m0, s58
	s_waitcnt vmcnt(0)
	v_add_f32_e32 v6, v6, v7
	global_load_lds_dwordx4 v[102:103], off
	v_add_f32_e32 v7, v8, v9
	v_add_f32_e32 v2, v2, v3
	v_add_f32_e32 v3, v4, v5
	v_add_f32_e32 v6, v6, v7
	v_add_f32_e32 v2, v2, v3
	v_add_f32_e32 v3, v6, v2
	v_mbcnt_lo_u32_b32 v2, -1, 0
	v_mbcnt_hi_u32_b32 v6, -1, v2
	v_and_b32_e32 v4, 64, v6
	v_xor_b32_e32 v2, 32, v6
	v_add_u32_e32 v7, 64, v4
	v_cmp_lt_i32_e32 vcc, v2, v7
	s_and_b32 s4, s33, 0x80
	s_and_b32 s5, s30, 0x3fffffc
	v_cndmask_b32_e32 v2, v6, v2, vcc
	v_lshlrev_b32_e32 v178, 2, v2
	s_lshl_b32 s4, s4, 2
	ds_bpermute_b32 v4, v178, v3
	v_and_or_b32 v102, v0, 16, s26
	s_add_i32 s4, s4, 0
	s_lshl_b32 s5, s5, 2
	s_add_i32 s4, s4, s5
	v_lshlrev_b32_e32 v103, 5, v0
	v_lshrrev_b32_e32 v2, 2, v102
	v_and_b32_e32 v103, 0x1e0, v103
	s_add_i32 s4, s4, 0x20000
	v_and_b32_e32 v2, 12, v2
	v_add3_u32 v2, s4, v103, v2
	v_cmp_eq_u32_e64 s[4:5], 0, v98
	s_and_saveexec_b64 s[26:27], s[4:5]
	s_cbranch_execz .LBB0_350
	s_waitcnt lgkmcnt(0)
	v_add_f32_e32 v3, v3, v4
	v_mov_b32_e32 v4, 0x358637bd
	v_fmac_f32_e32 v4, 0x3a800000, v3
	v_rsq_f32_e32 v3, v4
	ds_write_b32 v2, v3

; #define PG8_LAS __attribute__((address_space(3)))
; #define PG8_WAIT_V(n) asm volatile("s_waitcnt vmcnt(" #n ")" ::: "memory")
; #define PG8_BAR __builtin_amdgcn_s_barrier()
; #define S xcd_barrier(bar);
; template <class Epi, bool ALIGN_EPI, bool ABLK = false>
; __device__ __forceinline__ void gemm_phase(PG8_LAS unsigned char* lds, const Gemm g, const StaticOrder& S, const Epi& E) {
;     ...
;     const unsigned ldsw = (unsigned)wid * 1024u;
;     const int aoff = lds_byte(wr * 64 + fr, fq * 8), boff = lds_byte(wc * 32 + fr, fq * 8);
;     ...
;     Unit cur, nxt; int ui = 0;
;     if (!S.next(0, cur)) return;
;     Acc acc;
; #pragma unroll
;     for (int a = 0; a < 2; ++a)
; #pragma unroll
;         for (int b = 0; b < 2; ++b)
; #pragma unroll
;             for (int m = 0; m < 4; ++m)
; #pragma unroll
;                 for (int n = 0; n < 2; ++n) acc[a][b][m][n] = (f32x4){0.f, 0.f, 0.f, 0.f};
;     bf16x8 At[4][2], B0[2][2], B1[2][2];
;     const char* cA = PG8_ABASE(cur); const char* cB = PG8_BBASE(cur);
;     constexpr int RS_MAXT = 12;
;     PG8_LAS float* RS = (PG8_LAS float*)(lds + EX_OFF);
;     f32x4 rq[RS_MAXT][2];
;     if constexpr (Epi::RSTD_LDS) {
; #pragma unroll
;         for (int i = 0; i < RS_MAXT; ++i) { Unit t; if (S.next(i, t)) { const float* p = E.ssqp + (size_t)(t.pm * BM + wid * 32 + (lane & 31)) * 16 + (lane >> 5) * 8; rq[i][0] = *(const f32x4*)p; rq[i][1] = *(const f32x4*)(p + 4); } }
;     }
;     PG8_STAGE(PG8_SB(0, 0), cB, voffB); PG8_STAGE(PG8_SB(0, 1), cB + hstepB, voffB); PG8_STAGE(PG8_SA(0, 0), cA, voffA); PG8_STAGE(PG8_SA(0, 1), cA + hstepA, voffA);
;     if constexpr (Epi::RSTD_LDS) {
;         const int prow = wid * 32 + (lane & 31), slot = (((prow >> 6) & 1) * 16 + (prow & 15)) * 8 + (prow >> 7) * 4 + ((prow >> 4) & 3);
; #pragma unroll
;         for (int i = 0; i < RS_MAXT; ++i) { Unit t; if (S.next(i, t)) {
;             float sm = ((rq[i][0].x + rq[i][0].y) + (rq[i][0].z + rq[i][0].w)) + ((rq[i][1].x + rq[i][1].y) + (rq[i][1].z + rq[i][1].w));
;             sm += __shfl_xor(sm, 32);
;             if (lane < 32) RS[i * 256 + slot] = __builtin_amdgcn_rsqf(sm * (1.0f / D) + EPS); } }
;     }
;     if (wr == 1) PG8_BAR;
;     PG8_WAIT_V(2); PG8_BAR;
;     PG8_STAGE(PG8_SB(1, 0), cB + kstepB, voffB); PG8_STAGE(PG8_SA(1, 0), cA + kstepA, voffA); PG8_STAGE(PG8_SB(1, 1), cB + hstepB + kstepB, voffB);
;     PG8_WAIT_V(6); PG8_BAR;
.LBB0_396:
	s_and_b32 s5, s30, 3
	v_and_b32_e32 v8, 15, v0
	v_and_b32_e32 v9, 48, v0
	v_lshlrev_b32_e32 v11, 2, v0
	v_lshlrev_b32_e32 v13, 6, v0
	s_movk_i32 s29, 0x3c0
	v_lshl_or_b32 v10, v8, 6, v9
	v_and_b32_e32 v11, 32, v11
	s_lshl_b32 s28, s5, 12
	v_and_or_b32 v9, v13, s29, v9
	v_bitop3_b32 v180, s28, v9, v11 bitop3:0xf6
	s_mov_b64 s[28:29], 0x8000
	s_add_i32 m0, s55, 0x18000
	v_lshl_add_u64 v[2:3], v[2:3], 0, s[28:29]
	s_lshl_b32 s38, s4, 13
	s_lshl_b32 s17, s5, 5
	s_waitcnt vmcnt(2)
	s_barrier
	global_load_lds_dwordx4 v[2:3], off
	v_lshl_add_u64 v[2:3], v[4:5], 0, s[28:29]
	s_add_i32 m0, s55, 0x1a000
	s_mov_b64 s[30:31], 0x8000
	s_add_i32 s59, s55, 0x8000
	s_add_i32 s61, s55, 0xa000
	global_load_lds_dwordx4 v[2:3], off
	v_lshl_add_u64 v[2:3], v[100:101], 0, s[30:31]
	s_mov_b32 m0, s59
	s_mov_b64 s[34:35], 0xa000
	s_add_u32 s36, s22, 0xc000
	global_load_lds_dwordx4 v[2:3], off
	v_lshl_add_u64 v[2:3], v[100:101], 0, s[34:35]
	s_mov_b32 m0, s61
	s_addc_u32 s37, s23, 0
	global_load_lds_dwordx4 v[2:3], off
	s_add_i32 m0, s55, 0x1c000
	v_lshl_add_u64 v[2:3], s[36:37], 0, v[148:149]
	global_load_lds_dwordx4 v[2:3], off
	v_lshl_add_u64 v[2:3], s[36:37], 0, v[150:151]
	s_add_i32 m0, s55, 0x1e000
	s_cmpk_lt_u32 s33, 0x100
	global_load_lds_dwordx4 v[2:3], off
	v_and_b32_e32 v2, 12, v99
	v_lshlrev_b32_e32 v152, 2, v2
	v_mov_b32_e32 v153, 0
	s_cselect_b64 s[36:37], -1, 0
	v_lshl_add_u64 v[154:155], s[6:7], 0, v[152:153]
	s_lshl_b32 s6, s4, 9
	s_add_i32 s6, s6, 0
	v_lshl_or_b32 v179, s4, 6, v8
	s_add_i32 s6, s6, 0x20000
	s_lshl_b32 s4, s4, 3
	v_lshl_add_u32 v181, v8, 5, s6
	s_bfe_u32 s6, s33, 0x10006
	s_and_b32 s4, s4, 8
	s_or_b32 s6, s4, s6
	s_or_b32 s4, s4, s5
	s_lshl_b32 s4, s4, 10
	v_bitop3_b32 v2, v10, s4, v11 bitop3:0xde
	v_or_b32_e32 v156, 0x800, v2
	v_or_b32_e32 v160, 0x1800, v2
	v_xor_b32_e32 v2, 16, v6
	s_waitcnt vmcnt(6)
	s_lshl_b32 s6, s6, 10
	v_cmp_lt_i32_e32 vcc, v2, v7
	v_bitop3_b32 v12, v10, s38, v11 bitop3:0xde
	s_and_b32 s62, s38, 0x4000
	v_bitop3_b32 v152, v10, s6, v11 bitop3:0xde
	v_cndmask_b32_e32 v2, v6, v2, vcc
	s_mov_b32 s60, 0
	v_mov_b32_e32 v157, v153
	v_or_b32_e32 v158, 0x1000, v152
	v_mov_b32_e32 v159, v153
	v_mov_b32_e32 v161, v153
	s_xor_b32 s63, s62, 0x4000
	v_lshlrev_b32_e32 v182, 2, v2
	s_add_i32 s64, 0, 0x10000
	s_add_i32 s65, 0, 0x14000
	v_add_u32_e32 v183, 0, v12
	v_mov_b32_e32 v2, v153
	v_mov_b32_e32 v3, v153
	v_mov_b32_e32 v4, v153
	v_mov_b32_e32 v5, v153
	v_mov_b32_e32 v6, v153
	v_mov_b32_e32 v7, v153
	v_mov_b32_e32 v8, v153
	v_mov_b32_e32 v9, v153
	v_mov_b32_e32 v10, v153
	v_mov_b32_e32 v11, v153
	v_mov_b32_e32 v12, v153
	v_mov_b32_e32 v13, v153
	v_mov_b32_e32 v14, v153
	v_mov_b32_e32 v15, v153
	v_mov_b32_e32 v16, v153
	v_mov_b32_e32 v17, v153
	v_mov_b32_e32 v18, v153
	v_mov_b32_e32 v19, v153
	v_mov_b32_e32 v20, v153
	v_mov_b32_e32 v21, v153
	v_mov_b32_e32 v22, v153
	v_mov_b32_e32 v23, v153
	v_mov_b32_e32 v24, v153
	v_mov_b32_e32 v25, v153
	v_mov_b32_e32 v26, v153
	v_mov_b32_e32 v27, v153
	v_mov_b32_e32 v28, v153
	v_mov_b32_e32 v29, v153
	v_mov_b32_e32 v30, v153
	v_mov_b32_e32 v31, v153
	v_mov_b32_e32 v32, v153
	v_mov_b32_e32 v33, v153
	v_mov_b32_e32 v34, v153
	v_mov_b32_e32 v35, v153
	v_mov_b32_e32 v36, v153
	v_mov_b32_e32 v37, v153
	v_mov_b32_e32 v38, v153
	v_mov_b32_e32 v39, v153
	v_mov_b32_e32 v40, v153
	v_mov_b32_e32 v41, v153
	v_mov_b32_e32 v42, v153
	v_mov_b32_e32 v43, v153
	v_mov_b32_e32 v44, v153
	v_mov_b32_e32 v45, v153
	v_mov_b32_e32 v46, v153
	v_mov_b32_e32 v47, v153
	v_mov_b32_e32 v48, v153
	v_mov_b32_e32 v49, v153
	v_mov_b32_e32 v50, v153
	v_mov_b32_e32 v51, v153
	v_mov_b32_e32 v52, v153
	v_mov_b32_e32 v53, v153
	v_mov_b32_e32 v54, v153
	v_mov_b32_e32 v55, v153
	v_mov_b32_e32 v56, v153
	v_mov_b32_e32 v57, v153
	v_mov_b32_e32 v58, v153
	v_mov_b32_e32 v59, v153
	v_mov_b32_e32 v60, v153
	v_mov_b32_e32 v61, v153
	v_mov_b32_e32 v62, v153
	v_mov_b32_e32 v63, v153
	v_mov_b32_e32 v64, v153
	v_mov_b32_e32 v65, v153
	v_mov_b32_e32 v66, v153
	v_mov_b32_e32 v67, v153
	v_mov_b32_e32 v68, v153
	v_mov_b32_e32 v69, v153
	v_mov_b32_e32 v70, v153
	v_mov_b32_e32 v71, v153
	v_mov_b32_e32 v72, v153
	v_mov_b32_e32 v73, v153
	v_mov_b32_e32 v74, v153
	v_mov_b32_e32 v75, v153
	v_mov_b32_e32 v76, v153
	v_mov_b32_e32 v77, v153
	v_mov_b32_e32 v78, v153
	v_mov_b32_e32 v79, v153
	v_mov_b32_e32 v80, v153
	v_mov_b32_e32 v81, v153
	v_mov_b32_e32 v82, v153
	v_mov_b32_e32 v83, v153
	v_mov_b32_e32 v84, v153
	v_mov_b32_e32 v85, v153
	v_mov_b32_e32 v86, v153
	v_mov_b32_e32 v87, v153
	v_mov_b32_e32 v88, v153
	v_mov_b32_e32 v89, v153
	v_mov_b32_e32 v90, v153
	v_mov_b32_e32 v91, v153
	v_mov_b32_e32 v92, v153
	v_mov_b32_e32 v93, v153
	v_mov_b32_e32 v94, v153
	v_mov_b32_e32 v95, v153
	v_mov_b32_e32 v96, v153
	v_mov_b32_e32 v97, v153
	v_mov_b32_e32 v98, v153
	v_mov_b32_e32 v99, v153
	v_mov_b32_e32 v100, v153
	v_mov_b32_e32 v101, v153
	v_mov_b32_e32 v102, v153
	v_mov_b32_e32 v103, v153
	v_mov_b32_e32 v104, v153
	v_mov_b32_e32 v105, v153
	v_mov_b32_e32 v106, v153
	v_mov_b32_e32 v107, v153
	v_mov_b32_e32 v108, v153
	v_mov_b32_e32 v109, v153
	v_mov_b32_e32 v110, v153
	v_mov_b32_e32 v111, v153
	v_mov_b32_e32 v112, v153
	v_mov_b32_e32 v113, v153
	v_mov_b32_e32 v114, v153
	v_mov_b32_e32 v115, v153
	v_mov_b32_e32 v116, v153
	v_mov_b32_e32 v117, v153
	v_mov_b32_e32 v118, v153
	v_mov_b32_e32 v119, v153
	v_mov_b32_e32 v120, v153
	v_mov_b32_e32 v121, v153
	v_mov_b32_e32 v122, v153
	v_mov_b32_e32 v123, v153
	v_mov_b32_e32 v124, v153
	v_mov_b32_e32 v125, v153
	v_mov_b32_e32 v126, v153
	v_mov_b32_e32 v127, v153
	v_mov_b32_e32 v128, v153
	v_mov_b32_e32 v129, v153
	v_mov_b32_e32 v184, 0x358637bd
	v_mov_b64_e32 v[162:163], 0xb00
	v_mov_b64_e32 v[164:165], 0xaff
	s_barrier
	s_branch .LBB0_399

; #define PG8_STAGE(bufoff, gbase, voff) do { _Pragma("unroll") for (int _i = 0; _i < 2; ++_i) \
;         __builtin_amdgcn_global_load_lds((const unsigned*)((const char*)(gbase) + (voff)[_i]), (PG8_LAS unsigned*)(lds + (bufoff) + ldsw + _i * 8192), 16, 0, 0); } while (0)
; #define PG8_LDA(dst, b, h) do { _Pragma("unroll") for (int m = 0; m < 4; ++m) _Pragma("unroll") for (int k = 0; k < 2; ++k) dst[m][k] = *(const PG8_LAS bf16x8*)(lds + PG8_SA(b, h) + aoff + m * 2048 + k * 1024); } while (0)
; #define PG8_LDB(dst, b, h) do { _Pragma("unroll") for (int n = 0; n < 2; ++n) _Pragma("unroll") for (int k = 0; k < 2; ++k) dst[n][k] = *(const PG8_LAS bf16x8*)(lds + PG8_SB(b, h) + boff + n * 2048 + k * 1024); } while (0)
; #define PG8_MMA(ai, bj, At, Bt) do { __builtin_amdgcn_s_setprio(1); _Pragma("unroll") for (int m = 0; m < 4; ++m) _Pragma("unroll") for (int n = 0; n < 2; ++n) _Pragma("unroll") for (int k = 0; k < 2; ++k) \
;         acc[ai][bj][m][n] = __builtin_amdgcn_mfma_f32_16x16x32_bf16(Bt[n][k], At[m][k], acc[ai][bj][m][n], 0, 0, 0); __builtin_amdgcn_s_setprio(0); } while (0)
; #define PG8_BAR __builtin_amdgcn_s_barrier()
; template <class Epi, bool ALIGN_EPI, bool ABLK = false>
; __device__ __forceinline__ void gemm_phase(PG8_LAS unsigned char* lds, const Gemm g, const StaticOrder& S, const Epi& E) {
;     ...
;     for (;;) {
;         const bool has_next = S.next(ui + 1, nxt);
;         const char* nA = has_next ? PG8_ABASE(nxt) : cA; const char* nB = has_next ? PG8_BBASE(nxt) : cB;
;         for (int t = 0; t < nt; t += 2) {
;             const bool last = (t == nt - 2);
;             const char* a1 = cA + (size_t)(t + 1) * kstepA;
;             const char* a2 = last ? nA : cA + (size_t)(t + 2) * kstepA; const char* b2 = last ? nB : cB + (size_t)(t + 2) * kstepB;
;             const char* a3 = a2 + kstepA; const char* b3 = b2 + kstepB;
;             PG8_LDB(B0, 0, 0); PG8_LDB(B1, 0, 1); PG8_SCHED; PG8_LDA(At, 0, 0); PG8_STAGE(PG8_SA(1, 1), a1 + hstepA, voffA);
;             PG8_WAIT_V(8); PG8_WAIT_L(0); PG8_BAR; PG8_MMA(0, 0, At, B0); PG8_MMA(0, 1, At, B1); PG8_BAR; PG8_SCHED;
;             PG8_LDA(At, 0, 1); PG8_STAGE(PG8_SB(0, 0), b2, voffB); PG8_STAGE(PG8_SB(0, 1), b2 + hstepB, voffB); PG8_STAGE(PG8_SA(0, 0), a2, voffA);
;             PG8_WAIT_V(8); PG8_WAIT_L(0); PG8_BAR; PG8_MMA(1, 0, At, B0); PG8_MMA(1, 1, At, B1); PG8_BAR; PG8_SCHED;
.LBB0_401:
	s_ashr_i32 s41, s40, 31
	s_lshl_b64 s[42:43], s[40:41], 19
	s_add_u32 s42, s11, s42
	s_addc_u32 s43, s54, s43
	s_and_b64 s[44:45], s[6:7], exec
	s_cselect_b32 s41, s43, s25
	s_cselect_b32 s66, s42, s24
	s_ashr_i32 s39, s38, 31
	s_lshl_b64 s[44:45], s[38:39], 19
	s_add_u32 s44, s100, s44
	s_addc_u32 s45, s101, s45
	s_and_b64 s[46:47], s[6:7], exec
	s_cselect_b32 s39, s45, s23
	s_cselect_b32 s67, s44, s22
	s_add_u32 s68, s22, 0x10000
	s_addc_u32 s69, s23, 0
	s_mov_b32 s70, -2
	s_mov_b64 s[46:47], 0x10000
	v_mov_b64_e32 v[130:131], v[146:147]
.LBB0_402:
	v_add_u32_e32 v144, s64, v180
	ds_read_b128 v[132:135], v144
	ds_read_b128 v[136:139], v144 offset:1024
	ds_read_b128 v[140:143], v144 offset:2048
	ds_read_b128 v[186:189], v144 offset:3072
	v_add_u32_e32 v144, s65, v180
	ds_read_b128 v[190:193], v144
	ds_read_b128 v[194:197], v144 offset:1024
	ds_read_b128 v[198:201], v144 offset:2048
	ds_read_b128 v[202:205], v144 offset:3072
	s_add_u32 s48, s24, s46
	s_addc_u32 s49, s25, s47
	s_cmp_eq_u32 s70, 12
	s_cselect_b32 s73, s41, s49
	s_cselect_b32 s72, s66, s48
	s_cselect_b32 s49, s39, s69
	s_cselect_b32 s48, s67, s68
	v_lshl_add_u64 v[144:145], s[24:25], 0, v[130:131]
	s_mov_b64 s[74:75], 0xc000
	v_lshl_add_u64 v[238:239], v[144:145], 0, s[74:75]
	s_add_i32 m0, s55, 0xc000
	s_mov_b64 s[74:75], 0xe000
	ds_read_b128 v[206:209], v183
	ds_read_b128 v[210:213], v183 offset:1024
	ds_read_b128 v[214:217], v183 offset:2048
	ds_read_b128 v[218:221], v183 offset:3072
	ds_read_b128 v[222:225], v183 offset:4096
	ds_read_b128 v[226:229], v183 offset:5120
	ds_read_b128 v[230:233], v183 offset:6144
	ds_read_b128 v[234:237], v183 offset:7168
	global_load_lds_dwordx4 v[238:239], off
	v_lshl_add_u64 v[144:145], v[144:145], 0, s[74:75]
	s_add_i32 m0, s55, 0xe000
	s_nop 0
	global_load_lds_dwordx4 v[144:145], off
	s_waitcnt vmcnt(8)
	s_waitcnt lgkmcnt(0)
	s_barrier
	s_setprio 1
	s_waitcnt lgkmcnt(0)
	v_mfma_f32_16x16x32_bf16 v[126:129], v[132:135], v[206:209], v[126:129]
	v_mfma_f32_16x16x32_bf16 v[122:125], v[140:143], v[206:209], v[122:125]
	v_mfma_f32_16x16x32_bf16 v[118:121], v[132:135], v[214:217], v[118:121]
	v_mfma_f32_16x16x32_bf16 v[114:117], v[140:143], v[214:217], v[114:117]
	v_mfma_f32_16x16x32_bf16 v[110:113], v[132:135], v[222:225], v[110:113]
	v_mfma_f32_16x16x32_bf16 v[106:109], v[140:143], v[222:225], v[106:109]
	v_mfma_f32_16x16x32_bf16 v[102:105], v[132:135], v[230:233], v[102:105]
	v_mfma_f32_16x16x32_bf16 v[98:101], v[140:143], v[230:233], v[98:101]
	v_mfma_f32_16x16x32_bf16 v[126:129], v[136:139], v[210:213], v[126:129]
	v_mfma_f32_16x16x32_bf16 v[122:125], v[186:189], v[210:213], v[122:125]
	v_mfma_f32_16x16x32_bf16 v[118:121], v[136:139], v[218:221], v[118:121]
	v_mfma_f32_16x16x32_bf16 v[114:117], v[186:189], v[218:221], v[114:117]
	v_mfma_f32_16x16x32_bf16 v[110:113], v[136:139], v[226:229], v[110:113]
	v_mfma_f32_16x16x32_bf16 v[106:109], v[186:189], v[226:229], v[106:109]
	v_mfma_f32_16x16x32_bf16 v[102:105], v[136:139], v[234:237], v[102:105]
	v_mfma_f32_16x16x32_bf16 v[98:101], v[186:189], v[234:237], v[98:101]
	s_setprio 0
	s_setprio 1
	v_mfma_f32_16x16x32_bf16 v[94:97], v[190:193], v[206:209], v[94:97]
	v_mfma_f32_16x16x32_bf16 v[90:93], v[198:201], v[206:209], v[90:93]
	v_mfma_f32_16x16x32_bf16 v[86:89], v[190:193], v[214:217], v[86:89]
	v_mfma_f32_16x16x32_bf16 v[82:85], v[198:201], v[214:217], v[82:85]
	v_mfma_f32_16x16x32_bf16 v[78:81], v[190:193], v[222:225], v[78:81]
	v_mfma_f32_16x16x32_bf16 v[74:77], v[198:201], v[222:225], v[74:77]
	v_mfma_f32_16x16x32_bf16 v[70:73], v[190:193], v[230:233], v[70:73]
	v_mfma_f32_16x16x32_bf16 v[66:69], v[198:201], v[230:233], v[66:69]
	v_mfma_f32_16x16x32_bf16 v[94:97], v[194:197], v[210:213], v[94:97]
	v_mfma_f32_16x16x32_bf16 v[90:93], v[202:205], v[210:213], v[90:93]
	v_mfma_f32_16x16x32_bf16 v[86:89], v[194:197], v[218:221], v[86:89]
	v_mfma_f32_16x16x32_bf16 v[82:85], v[202:205], v[218:221], v[82:85]
	v_mfma_f32_16x16x32_bf16 v[78:81], v[194:197], v[226:229], v[78:81]
	v_mfma_f32_16x16x32_bf16 v[74:77], v[202:205], v[226:229], v[74:77]
	v_mfma_f32_16x16x32_bf16 v[70:73], v[194:197], v[234:237], v[70:73]
	v_mfma_f32_16x16x32_bf16 v[66:69], v[202:205], v[234:237], v[66:69]
	s_setprio 0
	s_barrier
	s_add_i32 s71, s64, s9
	v_lshl_add_u64 v[144:145], s[48:49], 0, v[148:149]
	s_mov_b32 m0, s71
	ds_read_b128 v[206:209], v183 offset:16384
	ds_read_b128 v[210:213], v183 offset:17408
	ds_read_b128 v[214:217], v183 offset:18432
	ds_read_b128 v[218:221], v183 offset:19456
	ds_read_b128 v[222:225], v183 offset:20480
	ds_read_b128 v[226:229], v183 offset:21504
	ds_read_b128 v[230:233], v183 offset:22528
	ds_read_b128 v[234:237], v183 offset:23552
	global_load_lds_dwordx4 v[144:145], off
	s_add_i32 m0, s71, 0x2000
	s_add_u32 s74, s48, 0x4000
	v_lshl_add_u64 v[238:239], s[48:49], 0, v[150:151]
	s_addc_u32 s75, s49, 0
	s_add_i32 s71, s65, s9
	global_load_lds_dwordx4 v[238:239], off
	v_lshl_add_u64 v[240:241], s[74:75], 0, v[148:149]
	s_mov_b32 m0, s71
	s_nop 0
	global_load_lds_dwordx4 v[240:241], off
	v_lshl_add_u64 v[240:241], s[74:75], 0, v[150:151]
	s_add_i32 m0, s71, 0x2000
	s_nop 0
	global_load_lds_dwordx4 v[240:241], off
	v_lshl_add_u64 v[240:241], s[72:73], 0, v[146:147]
	s_mov_b32 m0, s55
	s_mov_b64 s[72:73], 0x2000
	global_load_lds_dwordx4 v[240:241], off
	v_lshl_add_u64 v[242:243], v[240:241], 0, s[72:73]
	s_mov_b32 m0, s56
	s_nop 0
	global_load_lds_dwordx4 v[242:243], off
	s_waitcnt vmcnt(8)
	s_waitcnt lgkmcnt(0)
	s_barrier
; #define PG8_STAGE(bufoff, gbase, voff) do { _Pragma("unroll") for (int _i = 0; _i < 2; ++_i) \
;         __builtin_amdgcn_global_load_lds((const unsigned*)((const char*)(gbase) + (voff)[_i]), (PG8_LAS unsigned*)(lds + (bufoff) + ldsw + _i * 8192), 16, 0, 0); } while (0)
; #define PG8_LDA(dst, b, h) do { _Pragma("unroll") for (int m = 0; m < 4; ++m) _Pragma("unroll") for (int k = 0; k < 2; ++k) dst[m][k] = *(const PG8_LAS bf16x8*)(lds + PG8_SA(b, h) + aoff + m * 2048 + k * 1024); } while (0)
; #define PG8_LDB(dst, b, h) do { _Pragma("unroll") for (int n = 0; n < 2; ++n) _Pragma("unroll") for (int k = 0; k < 2; ++k) dst[n][k] = *(const PG8_LAS bf16x8*)(lds + PG8_SB(b, h) + boff + n * 2048 + k * 1024); } while (0)
; #define PG8_MMA(ai, bj, At, Bt) do { __builtin_amdgcn_s_setprio(1); _Pragma("unroll") for (int m = 0; m < 4; ++m) _Pragma("unroll") for (int n = 0; n < 2; ++n) _Pragma("unroll") for (int k = 0; k < 2; ++k) \
;         acc[ai][bj][m][n] = __builtin_amdgcn_mfma_f32_16x16x32_bf16(Bt[n][k], At[m][k], acc[ai][bj][m][n], 0, 0, 0); __builtin_amdgcn_s_setprio(0); } while (0)
; #define PG8_WAIT_V(n) asm volatile("s_waitcnt vmcnt(" #n ")" ::: "memory")
; #define PG8_WAIT_L(n) asm volatile("s_waitcnt lgkmcnt(" #n ")" ::: "memory")
; #define PG8_BAR __builtin_amdgcn_s_barrier()
; #define PG8_SCHED __builtin_amdgcn_sched_barrier(0)
; template <class Epi, bool ALIGN_EPI, bool ABLK = false>
; __device__ __forceinline__ void gemm_phase(PG8_LAS unsigned char* lds, const Gemm g, const StaticOrder& S, const Epi& E) {
;     ...
;             PG8_WAIT_V(8); PG8_WAIT_L(0); PG8_BAR; PG8_MMA(1, 0, At, B0); PG8_MMA(1, 1, At, B1); PG8_BAR; PG8_SCHED;
;             PG8_LDB(B0, 1, 0); PG8_LDB(B1, 1, 1); PG8_SCHED; PG8_LDA(At, 1, 0); PG8_STAGE(PG8_SA(0, 1), a2 + hstepA, voffA);
;             PG8_WAIT_V(8); PG8_WAIT_L(0); PG8_BAR; PG8_MMA(0, 0, At, B0); PG8_MMA(0, 1, At, B1); PG8_BAR; PG8_SCHED;
	s_setprio 1
	s_waitcnt lgkmcnt(0)
	v_mfma_f32_16x16x32_bf16 v[62:65], v[132:135], v[206:209], v[62:65]
	v_mfma_f32_16x16x32_bf16 v[58:61], v[140:143], v[206:209], v[58:61]
	v_mfma_f32_16x16x32_bf16 v[54:57], v[132:135], v[214:217], v[54:57]
	v_mfma_f32_16x16x32_bf16 v[50:53], v[140:143], v[214:217], v[50:53]
	v_mfma_f32_16x16x32_bf16 v[46:49], v[132:135], v[222:225], v[46:49]
	v_mfma_f32_16x16x32_bf16 v[42:45], v[140:143], v[222:225], v[42:45]
	v_mfma_f32_16x16x32_bf16 v[38:41], v[132:135], v[230:233], v[38:41]
	v_mfma_f32_16x16x32_bf16 v[34:37], v[140:143], v[230:233], v[34:37]
	v_mfma_f32_16x16x32_bf16 v[62:65], v[136:139], v[210:213], v[62:65]
	v_mfma_f32_16x16x32_bf16 v[58:61], v[186:189], v[210:213], v[58:61]
	v_mfma_f32_16x16x32_bf16 v[54:57], v[136:139], v[218:221], v[54:57]
	v_mfma_f32_16x16x32_bf16 v[50:53], v[186:189], v[218:221], v[50:53]
	v_mfma_f32_16x16x32_bf16 v[46:49], v[136:139], v[226:229], v[46:49]
	v_mfma_f32_16x16x32_bf16 v[42:45], v[186:189], v[226:229], v[42:45]
	v_mfma_f32_16x16x32_bf16 v[38:41], v[136:139], v[234:237], v[38:41]
	v_mfma_f32_16x16x32_bf16 v[34:37], v[186:189], v[234:237], v[34:37]
	s_setprio 0
	s_setprio 1
	v_mfma_f32_16x16x32_bf16 v[30:33], v[190:193], v[206:209], v[30:33]
	v_mfma_f32_16x16x32_bf16 v[26:29], v[198:201], v[206:209], v[26:29]
	v_mfma_f32_16x16x32_bf16 v[22:25], v[190:193], v[214:217], v[22:25]
	v_mfma_f32_16x16x32_bf16 v[18:21], v[198:201], v[214:217], v[18:21]
	v_mfma_f32_16x16x32_bf16 v[14:17], v[190:193], v[222:225], v[14:17]
	v_mfma_f32_16x16x32_bf16 v[10:13], v[198:201], v[222:225], v[10:13]
	v_mfma_f32_16x16x32_bf16 v[6:9], v[190:193], v[230:233], v[6:9]
	v_mfma_f32_16x16x32_bf16 v[2:5], v[198:201], v[230:233], v[2:5]
	v_mfma_f32_16x16x32_bf16 v[30:33], v[194:197], v[210:213], v[30:33]
	v_mfma_f32_16x16x32_bf16 v[26:29], v[202:205], v[210:213], v[26:29]
	v_mfma_f32_16x16x32_bf16 v[22:25], v[194:197], v[218:221], v[22:25]
	v_mfma_f32_16x16x32_bf16 v[18:21], v[202:205], v[218:221], v[18:21]
	v_mfma_f32_16x16x32_bf16 v[14:17], v[194:197], v[226:229], v[14:17]
	v_mfma_f32_16x16x32_bf16 v[10:13], v[202:205], v[226:229], v[10:13]
	v_mfma_f32_16x16x32_bf16 v[6:9], v[194:197], v[234:237], v[6:9]
	v_mfma_f32_16x16x32_bf16 v[2:5], v[202:205], v[234:237], v[2:5]
	s_setprio 0
	s_barrier
	s_add_i32 s71, 0, 0x18000
	v_add_u32_e32 v166, s71, v180
	s_add_i32 s74, 0, 0x1c000
	ds_read_b128 v[132:135], v166
	ds_read_b128 v[136:139], v166 offset:1024
	ds_read_b128 v[140:143], v166 offset:2048
	ds_read_b128 v[186:189], v166 offset:3072
	v_add_u32_e32 v166, s74, v180
	ds_read_b128 v[190:193], v166
	ds_read_b128 v[194:197], v166 offset:1024
	ds_read_b128 v[198:201], v166 offset:2048
	ds_read_b128 v[202:205], v166 offset:3072
	s_mov_b64 s[72:73], 0x4000
	s_mov_b32 m0, s57
	v_lshl_add_u64 v[242:243], v[240:241], 0, s[72:73]
	s_mov_b64 s[72:73], 0x6000
	ds_read_b128 v[206:209], v183 offset:32768
	ds_read_b128 v[210:213], v183 offset:33792
	ds_read_b128 v[214:217], v183 offset:34816
	ds_read_b128 v[218:221], v183 offset:35840
	ds_read_b128 v[222:225], v183 offset:36864
	ds_read_b128 v[226:229], v183 offset:37888
	ds_read_b128 v[230:233], v183 offset:38912
	ds_read_b128 v[234:237], v183 offset:39936
	global_load_lds_dwordx4 v[242:243], off
	v_lshl_add_u64 v[242:243], v[240:241], 0, s[72:73]
	s_mov_b32 m0, s58
	s_nop 0
	global_load_lds_dwordx4 v[242:243], off
	s_waitcnt vmcnt(8)
	s_waitcnt lgkmcnt(0)
	s_barrier
	s_setprio 1
	s_waitcnt lgkmcnt(0)
	v_mfma_f32_16x16x32_bf16 v[126:129], v[132:135], v[206:209], v[126:129]
	v_mfma_f32_16x16x32_bf16 v[122:125], v[140:143], v[206:209], v[122:125]
	v_mfma_f32_16x16x32_bf16 v[118:121], v[132:135], v[214:217], v[118:121]
	v_mfma_f32_16x16x32_bf16 v[114:117], v[140:143], v[214:217], v[114:117]
	v_mfma_f32_16x16x32_bf16 v[110:113], v[132:135], v[222:225], v[110:113]
	v_mfma_f32_16x16x32_bf16 v[106:109], v[140:143], v[222:225], v[106:109]
	v_mfma_f32_16x16x32_bf16 v[102:105], v[132:135], v[230:233], v[102:105]
	v_mfma_f32_16x16x32_bf16 v[98:101], v[140:143], v[230:233], v[98:101]
	v_mfma_f32_16x16x32_bf16 v[126:129], v[136:139], v[210:213], v[126:129]
	v_mfma_f32_16x16x32_bf16 v[122:125], v[186:189], v[210:213], v[122:125]
	v_mfma_f32_16x16x32_bf16 v[118:121], v[136:139], v[218:221], v[118:121]
	v_mfma_f32_16x16x32_bf16 v[114:117], v[186:189], v[218:221], v[114:117]
	v_mfma_f32_16x16x32_bf16 v[110:113], v[136:139], v[226:229], v[110:113]
	v_mfma_f32_16x16x32_bf16 v[106:109], v[186:189], v[226:229], v[106:109]
	v_mfma_f32_16x16x32_bf16 v[102:105], v[136:139], v[234:237], v[102:105]
	v_mfma_f32_16x16x32_bf16 v[98:101], v[186:189], v[234:237], v[98:101]
	s_setprio 0
	s_setprio 1
	v_mfma_f32_16x16x32_bf16 v[94:97], v[190:193], v[206:209], v[94:97]
	v_mfma_f32_16x16x32_bf16 v[90:93], v[198:201], v[206:209], v[90:93]
	v_mfma_f32_16x16x32_bf16 v[86:89], v[190:193], v[214:217], v[86:89]
	v_mfma_f32_16x16x32_bf16 v[82:85], v[198:201], v[214:217], v[82:85]
	v_mfma_f32_16x16x32_bf16 v[78:81], v[190:193], v[222:225], v[78:81]
	v_mfma_f32_16x16x32_bf16 v[74:77], v[198:201], v[222:225], v[74:77]
	v_mfma_f32_16x16x32_bf16 v[70:73], v[190:193], v[230:233], v[70:73]
	v_mfma_f32_16x16x32_bf16 v[66:69], v[198:201], v[230:233], v[66:69]
	v_mfma_f32_16x16x32_bf16 v[94:97], v[194:197], v[210:213], v[94:97]
	v_mfma_f32_16x16x32_bf16 v[90:93], v[202:205], v[210:213], v[90:93]
	v_mfma_f32_16x16x32_bf16 v[86:89], v[194:197], v[218:221], v[86:89]
	v_mfma_f32_16x16x32_bf16 v[82:85], v[202:205], v[218:221], v[82:85]
	v_mfma_f32_16x16x32_bf16 v[78:81], v[194:197], v[226:229], v[78:81]
	v_mfma_f32_16x16x32_bf16 v[74:77], v[202:205], v[226:229], v[74:77]
	v_mfma_f32_16x16x32_bf16 v[70:73], v[194:197], v[234:237], v[70:73]
	v_mfma_f32_16x16x32_bf16 v[66:69], v[202:205], v[234:237], v[66:69]
	s_setprio 0
	s_barrier
; #define PG8_STAGE(bufoff, gbase, voff) do { _Pragma("unroll") for (int _i = 0; _i < 2; ++_i) \
;         __builtin_amdgcn_global_load_lds((const unsigned*)((const char*)(gbase) + (voff)[_i]), (PG8_LAS unsigned*)(lds + (bufoff) + ldsw + _i * 8192), 16, 0, 0); } while (0)
; #define PG8_LDA(dst, b, h) do { _Pragma("unroll") for (int m = 0; m < 4; ++m) _Pragma("unroll") for (int k = 0; k < 2; ++k) dst[m][k] = *(const PG8_LAS bf16x8*)(lds + PG8_SA(b, h) + aoff + m * 2048 + k * 1024); } while (0)
; #define PG8_MMA(ai, bj, At, Bt) do { __builtin_amdgcn_s_setprio(1); _Pragma("unroll") for (int m = 0; m < 4; ++m) _Pragma("unroll") for (int n = 0; n < 2; ++n) _Pragma("unroll") for (int k = 0; k < 2; ++k) \
;         acc[ai][bj][m][n] = __builtin_amdgcn_mfma_f32_16x16x32_bf16(Bt[n][k], At[m][k], acc[ai][bj][m][n], 0, 0, 0); __builtin_amdgcn_s_setprio(0); } while (0)
; #define PG8_WAIT_V(n) asm volatile("s_waitcnt vmcnt(" #n ")" ::: "memory")
; #define PG8_WAIT_L(n) asm volatile("s_waitcnt lgkmcnt(" #n ")" ::: "memory")
; #define PG8_BAR __builtin_amdgcn_s_barrier()
; #define PG8_SCHED __builtin_amdgcn_sched_barrier(0)
; template <class Epi, bool ALIGN_EPI, bool ABLK = false>
; __device__ __forceinline__ void gemm_phase(PG8_LAS unsigned char* lds, const Gemm g, const StaticOrder& S, const Epi& E) {
;     ...
;         for (int t = 0; t < nt; t += 2) {
;     ...
;             PG8_LDA(At, 1, 1); PG8_STAGE(PG8_SB(1, 0), b3, voffB); PG8_STAGE(PG8_SB(1, 1), b3 + hstepB, voffB); PG8_STAGE(PG8_SA(1, 0), a3, voffA);
;             PG8_WAIT_V(8); PG8_WAIT_L(0); PG8_BAR; PG8_MMA(1, 0, At, B0); PG8_MMA(1, 1, At, B1); PG8_BAR; PG8_SCHED;
;         }
	s_add_i32 s71, s71, s9
	v_lshl_add_u64 v[144:145], v[144:145], 0, s[28:29]
	s_mov_b32 m0, s71
	ds_read_b128 v[206:209], v183 offset:49152
	ds_read_b128 v[210:213], v183 offset:50176
	ds_read_b128 v[214:217], v183 offset:51200
	ds_read_b128 v[218:221], v183 offset:52224
	ds_read_b128 v[222:225], v183 offset:53248
	ds_read_b128 v[226:229], v183 offset:54272
	ds_read_b128 v[230:233], v183 offset:55296
	ds_read_b128 v[234:237], v183 offset:56320
	global_load_lds_dwordx4 v[144:145], off
	s_add_i32 m0, s71, 0x2000
	s_add_u32 s48, s48, 0xc000
	v_lshl_add_u64 v[144:145], v[238:239], 0, s[28:29]
	s_addc_u32 s49, s49, 0
	s_add_i32 s71, s74, s9
	global_load_lds_dwordx4 v[144:145], off
	v_lshl_add_u64 v[144:145], s[48:49], 0, v[148:149]
	s_mov_b32 m0, s71
	s_nop 0
	global_load_lds_dwordx4 v[144:145], off
	v_lshl_add_u64 v[144:145], s[48:49], 0, v[150:151]
	s_add_i32 m0, s71, 0x2000
	s_nop 0
	global_load_lds_dwordx4 v[144:145], off
	v_lshl_add_u64 v[144:145], v[240:241], 0, s[30:31]
	s_mov_b32 m0, s59
	s_nop 0
	global_load_lds_dwordx4 v[144:145], off
	v_lshl_add_u64 v[144:145], v[240:241], 0, s[34:35]
	s_mov_b32 m0, s61
	s_nop 0
	global_load_lds_dwordx4 v[144:145], off
	s_waitcnt vmcnt(8)
	s_waitcnt lgkmcnt(0)
	s_barrier
	s_setprio 1
	s_waitcnt lgkmcnt(0)
	v_mfma_f32_16x16x32_bf16 v[62:65], v[132:135], v[206:209], v[62:65]
	v_mfma_f32_16x16x32_bf16 v[58:61], v[140:143], v[206:209], v[58:61]
	v_mfma_f32_16x16x32_bf16 v[54:57], v[132:135], v[214:217], v[54:57]
	v_mfma_f32_16x16x32_bf16 v[50:53], v[140:143], v[214:217], v[50:53]
	v_mfma_f32_16x16x32_bf16 v[46:49], v[132:135], v[222:225], v[46:49]
	v_mfma_f32_16x16x32_bf16 v[42:45], v[140:143], v[222:225], v[42:45]
	v_mfma_f32_16x16x32_bf16 v[38:41], v[132:135], v[230:233], v[38:41]
	v_mfma_f32_16x16x32_bf16 v[34:37], v[140:143], v[230:233], v[34:37]
	v_mfma_f32_16x16x32_bf16 v[62:65], v[136:139], v[210:213], v[62:65]
	v_mfma_f32_16x16x32_bf16 v[58:61], v[186:189], v[210:213], v[58:61]
	v_mfma_f32_16x16x32_bf16 v[54:57], v[136:139], v[218:221], v[54:57]
	v_mfma_f32_16x16x32_bf16 v[50:53], v[186:189], v[218:221], v[50:53]
	v_mfma_f32_16x16x32_bf16 v[46:49], v[136:139], v[226:229], v[46:49]
	v_mfma_f32_16x16x32_bf16 v[42:45], v[186:189], v[226:229], v[42:45]
	v_mfma_f32_16x16x32_bf16 v[38:41], v[136:139], v[234:237], v[38:41]
	v_mfma_f32_16x16x32_bf16 v[34:37], v[186:189], v[234:237], v[34:37]
	s_setprio 0
	s_setprio 1
	v_mfma_f32_16x16x32_bf16 v[30:33], v[190:193], v[206:209], v[30:33]
	v_mfma_f32_16x16x32_bf16 v[26:29], v[198:201], v[206:209], v[26:29]
	v_mfma_f32_16x16x32_bf16 v[22:25], v[190:193], v[214:217], v[22:25]
	v_mfma_f32_16x16x32_bf16 v[18:21], v[198:201], v[214:217], v[18:21]
	v_mfma_f32_16x16x32_bf16 v[14:17], v[190:193], v[222:225], v[14:17]
	v_mfma_f32_16x16x32_bf16 v[10:13], v[198:201], v[222:225], v[10:13]
	v_mfma_f32_16x16x32_bf16 v[6:9], v[190:193], v[230:233], v[6:9]
	v_mfma_f32_16x16x32_bf16 v[2:5], v[198:201], v[230:233], v[2:5]
	v_mfma_f32_16x16x32_bf16 v[30:33], v[194:197], v[210:213], v[30:33]
	v_mfma_f32_16x16x32_bf16 v[26:29], v[202:205], v[210:213], v[26:29]
	v_mfma_f32_16x16x32_bf16 v[22:25], v[194:197], v[218:221], v[22:25]
	v_mfma_f32_16x16x32_bf16 v[18:21], v[202:205], v[218:221], v[18:21]
	v_mfma_f32_16x16x32_bf16 v[14:17], v[194:197], v[226:229], v[14:17]
	v_mfma_f32_16x16x32_bf16 v[10:13], v[202:205], v[226:229], v[10:13]
	v_mfma_f32_16x16x32_bf16 v[6:9], v[194:197], v[234:237], v[6:9]
	v_mfma_f32_16x16x32_bf16 v[2:5], v[202:205], v[234:237], v[2:5]
	s_setprio 0
	s_barrier
	s_add_i32 s70, s70, 2
	s_add_u32 s68, s68, 0x10000
	s_addc_u32 s69, s69, 0
	s_add_u32 s46, s46, 0x10000
	s_addc_u32 s47, s47, 0
	s_mov_b64 s[48:49], 0x10000
	s_cmp_gt_u32 s70, 13
	v_lshl_add_u64 v[130:131], v[130:131], 0, s[48:49]
	s_cbranch_scc0 .LBB0_402
	s_and_b64 vcc, exec, s[36:37]
	s_cbranch_vccz .LBB0_405
	s_barrier

; #define LAS __attribute__((address_space(3)))
; __device__ __forceinline__ unsigned pk2(float lo, float hi) { f32x2_t v = {lo, hi}; bf16x2_t b = __builtin_convertvector(v, bf16x2_t); return __builtin_bit_cast(unsigned, b); }
; __device__ __forceinline__ float fast_rcp(float x) { return __builtin_amdgcn_rcpf(x); }
; __device__ __forceinline__ void swa_p_compute(SwaRegs& R, const Args& a, Frame& F, int u) {
;     ...
;         for (int kb = 0; kb < 6; ++kb) if (kb >= kb0) {
;             v2u vlo[2][2], vhi[2][2];
; #pragma unroll
;             for (int s2 = 0; s2 < 2; ++s2)
; #pragma unroll
;                 for (int db = 0; db < 2; ++db) {
;                     const LAS unsigned char* vp = Vl + (db * 32 + r32) * SWA_VLD_B + (kb * 32 + s2 * 16 + 4 * hi) * 2;
;                     vlo[s2][db] = *(const LAS v2u*)vp; vhi[s2][db] = *(const LAS v2u*)(vp + 16);
;                 }
;             bf16x8 pb[2];
; #pragma unroll
;             for (int s2 = 0; s2 < 2; ++s2) {
;                 v4u pw; pw.x = pk2(sacc[kb][8 * s2 + 0], sacc[kb][8 * s2 + 1]); pw.y = pk2(sacc[kb][8 * s2 + 2], sacc[kb][8 * s2 + 3]);
;                 pw.z = pk2(sacc[kb][8 * s2 + 4], sacc[kb][8 * s2 + 5]); pw.w = pk2(sacc[kb][8 * s2 + 6], sacc[kb][8 * s2 + 7]);
;                 pb[s2] = __builtin_bit_cast(bf16x8, pw);
;             }
;             asm volatile("s_waitcnt lgkmcnt(0)" ::: "memory"); __builtin_amdgcn_sched_barrier(0);
; #pragma unroll
;             for (int s2 = 0; s2 < 2; ++s2)
; #pragma unroll
;                 for (int db = 0; db < 2; ++db) {
;                     v4u av; av.x = vlo[s2][db].x; av.y = vlo[s2][db].y; av.z = vhi[s2][db].x; av.w = vhi[s2][db].y;
;                     o[db] = __builtin_amdgcn_mfma_f32_32x32x16_bf16(__builtin_bit_cast(bf16x8, av), pb[s2], o[db], 0, 0, 0);
;                 }
;             __builtin_amdgcn_sched_barrier(0);
;         }
;         const float inv = fast_rcp(l);
; #pragma unroll
;         for (int db = 0; db < 2; ++db)
; #pragma unroll
;             for (int g4 = 0; g4 < 4; ++g4) {
;                 v2u w; w.x = pk2(o[db][4 * g4 + 0] * inv, o[db][4 * g4 + 1] * inv); w.y = pk2(o[db][4 * g4 + 2] * inv, o[db][4 * g4 + 3] * inv);
;                 *(v2u*)(qrow + db * 32 + 8 * g4 + 4 * hi) = w;
;             }
.LBB0_1442:
	ds_read2_b64 v[230:233], v198 offset0:160 offset1:162
	ds_read2_b64 v[234:237], v198 offset0:164 offset1:166
	ds_read2_b64 v[238:241], v197 offset0:192 offset1:194
	ds_read2_b64 v[242:245], v197 offset0:196 offset1:198
	s_waitcnt lgkmcnt(0)
	v_sub_f32_e32 v162, v199, v162
	s_waitcnt lgkmcnt(4)
	v_add_f32_e32 v183, v163, v184
	v_lshlrev_b32_e32 v184, 1, v182
	v_mov_b32_e32 v185, v171
	v_exp_f32_e32 v254, v162
	v_lshl_add_u64 v[162:163], v[186:187], 0, v[184:185]
	v_cvt_pk_bf16_f32 v246, v164, v165
	v_cvt_pk_bf16_f32 v247, v201, v204
	v_cvt_pk_bf16_f32 v248, v209, v214
	v_cvt_pk_bf16_f32 v249, v216, v219
	v_cvt_pk_bf16_f32 v250, v221, v223
	v_cvt_pk_bf16_f32 v251, v224, v225
	v_cvt_pk_bf16_f32 v252, v226, v227
	v_cvt_pk_bf16_f32 v253, v228, v229
	s_waitcnt lgkmcnt(3)
	v_mfma_f32_32x32x16_bf16 v[82:97], v[230:233], v[246:249], v[82:97]
	s_waitcnt lgkmcnt(1)
	v_mfma_f32_32x32x16_bf16 v[66:81], v[238:241], v[246:249], v[66:81]
	v_mfma_f32_32x32x16_bf16 v[82:97], v[234:237], v[250:253], v[82:97]
	s_waitcnt lgkmcnt(0)
	v_mfma_f32_32x32x16_bf16 v[66:81], v[242:245], v[250:253], v[66:81]
	ds_read2_b64 v[224:227], v198 offset0:168 offset1:170
	ds_read2_b64 v[228:231], v198 offset0:172 offset1:174
	ds_read2_b64 v[232:235], v197 offset0:200 offset1:202
	ds_read2_b64 v[236:239], v197 offset0:204 offset1:206
	s_waitcnt lgkmcnt(0)
	v_cvt_pk_bf16_f32 v200, v200, v202
	v_cvt_pk_bf16_f32 v201, v203, v205
	v_cvt_pk_bf16_f32 v202, v206, v207
	v_cvt_pk_bf16_f32 v203, v210, v212
	v_cvt_pk_bf16_f32 v204, v208, v211
	v_cvt_pk_bf16_f32 v205, v213, v215
	v_cvt_pk_bf16_f32 v206, v217, v218
	v_cvt_pk_bf16_f32 v207, v220, v222
	s_waitcnt lgkmcnt(3)
	v_mfma_f32_32x32x16_bf16 v[82:97], v[224:227], v[200:203], v[82:97]
	s_waitcnt lgkmcnt(1)
	v_mfma_f32_32x32x16_bf16 v[66:81], v[232:235], v[200:203], v[66:81]
	v_mfma_f32_32x32x16_bf16 v[82:97], v[228:231], v[204:207], v[82:97]
	s_waitcnt lgkmcnt(0)
	v_mfma_f32_32x32x16_bf16 v[66:81], v[236:239], v[204:207], v[66:81]
	v_add_f32_e32 v164, v254, v183
	v_rcp_f32_e32 v164, v164
	s_and_b64 vcc, exec, s[6:7]
	s_nop 8
	v_pk_mul_f32 v[66:67], v[164:165], v[66:67] op_sel_hi:[0,1]
	v_pk_mul_f32 v[68:69], v[164:165], v[68:69] op_sel_hi:[0,1]
	v_pk_mul_f32 v[82:83], v[164:165], v[82:83] op_sel_hi:[0,1]
	v_pk_mul_f32 v[84:85], v[164:165], v[84:85] op_sel_hi:[0,1]
	v_cvt_pk_bf16_f32 v66, v66, v67
	v_cvt_pk_bf16_f32 v67, v68, v69
	v_pk_mul_f32 v[86:87], v[164:165], v[86:87] op_sel_hi:[0,1]
	v_cvt_pk_bf16_f32 v82, v82, v83
	v_cvt_pk_bf16_f32 v83, v84, v85
	v_pk_mul_f32 v[84:85], v[164:165], v[88:89] op_sel_hi:[0,1]
	global_store_dwordx2 v[162:163], v[66:67], off offset:64
	v_pk_mul_f32 v[66:67], v[164:165], v[70:71] op_sel_hi:[0,1]
	v_pk_mul_f32 v[68:69], v[164:165], v[72:73] op_sel_hi:[0,1]
	global_store_dwordx2 v[162:163], v[82:83], off
	v_cvt_pk_bf16_f32 v82, v86, v87
	v_cvt_pk_bf16_f32 v83, v84, v85
	v_cvt_pk_bf16_f32 v66, v66, v67
	v_cvt_pk_bf16_f32 v67, v68, v69
	global_store_dwordx2 v[162:163], v[82:83], off offset:16
	v_pk_mul_f32 v[82:83], v[164:165], v[90:91] op_sel_hi:[0,1]
	v_pk_mul_f32 v[84:85], v[164:165], v[92:93] op_sel_hi:[0,1]
	global_store_dwordx2 v[162:163], v[66:67], off offset:80
	v_pk_mul_f32 v[66:67], v[164:165], v[74:75] op_sel_hi:[0,1]
	v_pk_mul_f32 v[68:69], v[164:165], v[76:77] op_sel_hi:[0,1]
	v_cvt_pk_bf16_f32 v82, v82, v83
	v_cvt_pk_bf16_f32 v83, v84, v85
	v_cvt_pk_bf16_f32 v66, v66, v67
	v_cvt_pk_bf16_f32 v67, v68, v69
	global_store_dwordx2 v[162:163], v[82:83], off offset:32
	v_pk_mul_f32 v[82:83], v[164:165], v[94:95] op_sel_hi:[0,1]
	v_pk_mul_f32 v[84:85], v[164:165], v[96:97] op_sel_hi:[0,1]
	global_store_dwordx2 v[162:163], v[66:67], off offset:96
	v_pk_mul_f32 v[66:67], v[164:165], v[78:79] op_sel_hi:[0,1]
	v_pk_mul_f32 v[68:69], v[164:165], v[80:81] op_sel_hi:[0,1]
	v_cvt_pk_bf16_f32 v82, v82, v83
	v_cvt_pk_bf16_f32 v83, v84, v85
	v_cvt_pk_bf16_f32 v66, v66, v67
	v_cvt_pk_bf16_f32 v67, v68, v69
	global_store_dwordx2 v[162:163], v[82:83], off offset:48
	global_store_dwordx2 v[162:163], v[66:67], off offset:112
	s_cbranch_vccz .LBB0_1452
	s_and_b64 vcc, exec, s[6:7]
	s_cbranch_vccz .LBB0_1453

; #define LAS __attribute__((address_space(3)))
; __device__ __forceinline__ void swa_p_compute(SwaRegs& R, const Args& a, Frame& F, int u) {
;     ...
;         for (int kb = 0; kb < 6; ++kb) {
;             if (kb >= kb0) {
;                 f32x16 c = {0.f, 0.f, 0.f, 0.f, 0.f, 0.f, 0.f, 0.f, 0.f, 0.f, 0.f, 0.f, 0.f, 0.f, 0.f, 0.f};
;                 bf16x8 kf[4];
; #pragma unroll
;                 for (int s = 0; s < 4; ++s) kf[s] = *(const LAS bf16x8*)(Kl + (kb * 32 + r32) * SWA_KLD_B + s * 32 + hi * 16);
; #pragma unroll
;                 for (int s = 0; s < 4; ++s) c = __builtin_amdgcn_mfma_f32_32x32x16_bf16(kf[s], qf[tb][s], c, 0, 0, 0);
;                 sacc[kb] = c;
;             }
.LBB0_1445:
	ds_read_b128 v[2:5], v175 offset:9216
	ds_read_b128 v[66:69], v175 offset:9248
	s_waitcnt vmcnt(9) lgkmcnt(1)
	v_mfma_f32_32x32x16_bf16 v[2:17], v[2:5], v[158:161], 0
	s_waitcnt lgkmcnt(0)
	v_mfma_f32_32x32x16_bf16 v[2:17], v[66:69], v[154:157], v[2:17]
	ds_read_b128 v[66:69], v175 offset:9280
	ds_read_b128 v[70:73], v175 offset:9312
	s_waitcnt lgkmcnt(1)
	v_mfma_f32_32x32x16_bf16 v[2:17], v[66:69], v[150:153], v[2:17]
	s_waitcnt vmcnt(8) lgkmcnt(0)
	v_mfma_f32_32x32x16_bf16 v[2:17], v[70:73], v[146:149], v[2:17]
	s_mov_b64 s[22:23], -1
	s_and_b64 vcc, exec, s[20:21]
	s_cbranch_vccnz .LBB0_1455

; #define LAS __attribute__((address_space(3)))
; __device__ __forceinline__ void swa_p_compute(SwaRegs& R, const Args& a, Frame& F, int u) {
;     ...
;         for (int kb = 0; kb < 6; ++kb) {
;             if (kb >= kb0) {
;                 f32x16 c = {0.f, 0.f, 0.f, 0.f, 0.f, 0.f, 0.f, 0.f, 0.f, 0.f, 0.f, 0.f, 0.f, 0.f, 0.f, 0.f};
;                 bf16x8 kf[4];
; #pragma unroll
;                 for (int s = 0; s < 4; ++s) kf[s] = *(const LAS bf16x8*)(Kl + (kb * 32 + r32) * SWA_KLD_B + s * 32 + hi * 16);
; #pragma unroll
;                 for (int s = 0; s < 4; ++s) c = __builtin_amdgcn_mfma_f32_32x32x16_bf16(kf[s], qf[tb][s], c, 0, 0, 0);
;                 sacc[kb] = c;
;             }
.LBB0_1448:
	ds_read_b128 v[50:53], v175 offset:18432
	ds_read_b128 v[54:57], v175 offset:18464
	s_and_b64 vcc, exec, s[6:7]
	s_waitcnt vmcnt(9) lgkmcnt(1)
	v_mfma_f32_32x32x16_bf16 v[82:97], v[50:53], v[158:161], 0
	s_waitcnt lgkmcnt(0)
	v_mfma_f32_32x32x16_bf16 v[82:97], v[54:57], v[154:157], v[82:97]
	ds_read_b128 v[50:53], v175 offset:18496
	ds_read_b128 v[54:57], v175 offset:18528
	s_waitcnt lgkmcnt(1)
	v_mfma_f32_32x32x16_bf16 v[82:97], v[50:53], v[150:153], v[82:97]
	ds_read_b128 v[50:53], v175 offset:23040
	ds_read_b128 v[200:203], v175 offset:23072
	s_waitcnt vmcnt(8) lgkmcnt(2)
	v_mfma_f32_32x32x16_bf16 v[82:97], v[54:57], v[146:149], v[82:97]
	s_waitcnt lgkmcnt(1)
	v_mfma_f32_32x32x16_bf16 v[50:65], v[50:53], v[158:161], 0
	s_waitcnt lgkmcnt(0)
	v_mfma_f32_32x32x16_bf16 v[50:65], v[200:203], v[154:157], v[50:65]
	ds_read_b128 v[154:157], v175 offset:23104
	ds_read_b128 v[158:161], v175 offset:23136
	s_waitcnt lgkmcnt(1)
	v_mfma_f32_32x32x16_bf16 v[50:65], v[154:157], v[150:153], v[50:65]
	v_mov_b32_e32 v150, v199
	s_waitcnt lgkmcnt(0)
	v_mfma_f32_32x32x16_bf16 v[50:65], v[158:161], v[146:149], v[50:65]
	s_cbranch_vccz .LBB0_1456
	s_and_b64 vcc, exec, s[6:7]
	s_cbranch_vccz .LBB0_1457

; #define LAS __attribute__((address_space(3)))
; __device__ __forceinline__ void swa_p_compute(SwaRegs& R, const Args& a, Frame& F, int u) {
;     ...
;         for (int kb = 0; kb < 6; ++kb) {
;             if (kb >= kb0) {
;                 f32x16 c = {0.f, 0.f, 0.f, 0.f, 0.f, 0.f, 0.f, 0.f, 0.f, 0.f, 0.f, 0.f, 0.f, 0.f, 0.f, 0.f};
;                 bf16x8 kf[4];
; #pragma unroll
;                 for (int s = 0; s < 4; ++s) kf[s] = *(const LAS bf16x8*)(Kl + (kb * 32 + r32) * SWA_KLD_B + s * 32 + hi * 16);
; #pragma unroll
;                 for (int s = 0; s < 4; ++s) c = __builtin_amdgcn_mfma_f32_32x32x16_bf16(kf[s], qf[tb][s], c, 0, 0, 0);
;                 sacc[kb] = c;
;             }
.LBB0_1452:
	ds_read_b128 v[34:37], v175
	ds_read_b128 v[66:69], v175 offset:32
	s_waitcnt vmcnt(9) lgkmcnt(1)
	v_mfma_f32_32x32x16_bf16 v[34:49], v[34:37], v[158:161], 0
	s_waitcnt lgkmcnt(0)
	v_mfma_f32_32x32x16_bf16 v[34:49], v[66:69], v[154:157], v[34:49]
	ds_read_b128 v[66:69], v175 offset:64
	ds_read_b128 v[70:73], v175 offset:96
	s_waitcnt lgkmcnt(1)
	v_mfma_f32_32x32x16_bf16 v[34:49], v[66:69], v[150:153], v[34:49]
	s_waitcnt vmcnt(8) lgkmcnt(0)
	v_mfma_f32_32x32x16_bf16 v[34:49], v[70:73], v[146:149], v[34:49]
	s_and_b64 vcc, exec, s[6:7]
	s_cbranch_vccnz .LBB0_1444
.LBB0_1453:
	ds_read_b128 v[18:21], v175 offset:4608
	ds_read_b128 v[66:69], v175 offset:4640
	s_waitcnt vmcnt(9) lgkmcnt(1)
	v_mfma_f32_32x32x16_bf16 v[18:33], v[18:21], v[158:161], 0
	s_waitcnt lgkmcnt(0)
	v_mfma_f32_32x32x16_bf16 v[18:33], v[66:69], v[154:157], v[18:33]
	ds_read_b128 v[66:69], v175 offset:4672
	ds_read_b128 v[70:73], v175 offset:4704
	s_waitcnt lgkmcnt(1)
	v_mfma_f32_32x32x16_bf16 v[18:33], v[66:69], v[150:153], v[18:33]
	s_waitcnt vmcnt(8) lgkmcnt(0)
	v_mfma_f32_32x32x16_bf16 v[18:33], v[70:73], v[146:149], v[18:33]
	s_and_b64 vcc, exec, s[10:11]
	s_cbranch_vccz .LBB0_1445

; #define LAS __attribute__((address_space(3)))
; __device__ __forceinline__ void swa_p_compute(SwaRegs& R, const Args& a, Frame& F, int u) {
;     ...
;         for (int kb = 0; kb < 6; ++kb) {
;             if (kb >= kb0) {
;                 f32x16 c = {0.f, 0.f, 0.f, 0.f, 0.f, 0.f, 0.f, 0.f, 0.f, 0.f, 0.f, 0.f, 0.f, 0.f, 0.f, 0.f};
;                 bf16x8 kf[4];
; #pragma unroll
;                 for (int s = 0; s < 4; ++s) kf[s] = *(const LAS bf16x8*)(Kl + (kb * 32 + r32) * SWA_KLD_B + s * 32 + hi * 16);
; #pragma unroll
;                 for (int s = 0; s < 4; ++s) c = __builtin_amdgcn_mfma_f32_32x32x16_bf16(kf[s], qf[tb][s], c, 0, 0, 0);
;                 sacc[kb] = c;
;             }
.LBB0_1455:
	ds_read_b128 v[66:69], v175 offset:13824
	ds_read_b128 v[82:85], v175 offset:13856
	s_waitcnt vmcnt(9) lgkmcnt(1)
	v_mfma_f32_32x32x16_bf16 v[66:81], v[66:69], v[158:161], 0
	s_waitcnt lgkmcnt(0)
	v_mfma_f32_32x32x16_bf16 v[66:81], v[82:85], v[154:157], v[66:81]
	ds_read_b128 v[82:85], v175 offset:13888
	ds_read_b128 v[86:89], v175 offset:13920
	s_waitcnt lgkmcnt(1)
	v_mfma_f32_32x32x16_bf16 v[66:81], v[82:85], v[150:153], v[66:81]
	s_waitcnt vmcnt(8) lgkmcnt(0)
	v_mfma_f32_32x32x16_bf16 v[66:81], v[86:89], v[146:149], v[66:81]
	s_cbranch_execz .LBB0_1447
	s_branch .LBB0_1448

; #define LAS __attribute__((address_space(3)))
; __device__ __forceinline__ void swa_p_compute(SwaRegs& R, const Args& a, Frame& F, int u) {
;     ...
;         for (int kb = 0; kb < 6; ++kb) if (kb >= kb0) {
;             v2u vlo[2][2], vhi[2][2];
; #pragma unroll
;             for (int s2 = 0; s2 < 2; ++s2)
; #pragma unroll
;                 for (int db = 0; db < 2; ++db) {
;                     const LAS unsigned char* vp = Vl + (db * 32 + r32) * SWA_VLD_B + (kb * 32 + s2 * 16 + 4 * hi) * 2;
;                     vlo[s2][db] = *(const LAS v2u*)vp; vhi[s2][db] = *(const LAS v2u*)(vp + 16);
;                 }
;             bf16x8 pb[2];
; #pragma unroll
;             for (int s2 = 0; s2 < 2; ++s2) {
;                 v4u pw; pw.x = pk2(sacc[kb][8 * s2 + 0], sacc[kb][8 * s2 + 1]); pw.y = pk2(sacc[kb][8 * s2 + 2], sacc[kb][8 * s2 + 3]);
;                 pw.z = pk2(sacc[kb][8 * s2 + 4], sacc[kb][8 * s2 + 5]); pw.w = pk2(sacc[kb][8 * s2 + 6], sacc[kb][8 * s2 + 7]);
;                 pb[s2] = __builtin_bit_cast(bf16x8, pw);
;             }
;             asm volatile("s_waitcnt lgkmcnt(0)" ::: "memory"); __builtin_amdgcn_sched_barrier(0);
; #pragma unroll
;             for (int s2 = 0; s2 < 2; ++s2)
; #pragma unroll
;                 for (int db = 0; db < 2; ++db) {
;                     v4u av; av.x = vlo[s2][db].x; av.y = vlo[s2][db].y; av.z = vhi[s2][db].x; av.w = vhi[s2][db].y;
;                     o[db] = __builtin_amdgcn_mfma_f32_32x32x16_bf16(__builtin_bit_cast(bf16x8, av), pb[s2], o[db], 0, 0, 0);
;                 }
;             __builtin_amdgcn_sched_barrier(0);
;         }
;         const float inv = fast_rcp(l);
; #pragma unroll
;         for (int db = 0; db < 2; ++db)
; #pragma unroll
;             for (int g4 = 0; g4 < 4; ++g4) {
;                 v2u w; w.x = pk2(o[db][4 * g4 + 0] * inv, o[db][4 * g4 + 1] * inv); w.y = pk2(o[db][4 * g4 + 2] * inv, o[db][4 * g4 + 3] * inv);
;                 *(v2u*)(qrow + db * 32 + 8 * g4 + 4 * hi) = w;
;             }
; template <int K> __device__ __forceinline__ void run_phase(const Args& args, LAS unsigned char* ldsp) {
;     ...
;             if (F.tid == 0) qslot[2] = tn;
;             LDS_BAR();
;             const int u2 = (int)qslot[2];
;             if (u1 >= NSWA_P) break;
;             if (F.tid == 0) tn = __hip_atomic_fetch_add(qhead, 1u, __ATOMIC_RELAXED, __HIP_MEMORY_SCOPE_AGENT);
.LBB0_1476:
	ds_read2_b64 v[2:5], v198 offset0:160 offset1:162
	ds_read2_b64 v[6:9], v198 offset0:164 offset1:166
	ds_read2_b64 v[10:13], v197 offset0:192 offset1:194
	ds_read2_b64 v[14:17], v197 offset0:196 offset1:198
	s_waitcnt lgkmcnt(0)
	v_cvt_pk_bf16_f32 v18, v82, v83
	v_cvt_pk_bf16_f32 v19, v147, v148
	v_cvt_pk_bf16_f32 v20, v149, v150
	v_cvt_pk_bf16_f32 v21, v151, v154
	v_cvt_pk_bf16_f32 v22, v156, v158
	v_cvt_pk_bf16_f32 v23, v159, v160
	v_cvt_pk_bf16_f32 v24, v161, v164
	v_cvt_pk_bf16_f32 v25, v165, v185
	s_waitcnt lgkmcnt(3)
	v_mfma_f32_32x32x16_bf16 v[50:65], v[2:5], v[18:21], v[50:65]
	s_waitcnt lgkmcnt(1)
	v_mfma_f32_32x32x16_bf16 v[34:49], v[10:13], v[18:21], v[34:49]
	v_mfma_f32_32x32x16_bf16 v[50:65], v[6:9], v[22:25], v[50:65]
	s_waitcnt lgkmcnt(0)
	v_mfma_f32_32x32x16_bf16 v[34:49], v[14:17], v[22:25], v[34:49]
	ds_read2_b64 v[2:5], v198 offset0:168 offset1:170
	ds_read2_b64 v[6:9], v198 offset0:172 offset1:174
	ds_read2_b64 v[10:13], v197 offset0:200 offset1:202
	ds_read2_b64 v[14:17], v197 offset0:204 offset1:206
	s_waitcnt lgkmcnt(0)
	v_cvt_pk_bf16_f32 v18, v84, v87
	v_cvt_pk_bf16_f32 v19, v88, v89
	v_cvt_pk_bf16_f32 v20, v90, v91
	v_cvt_pk_bf16_f32 v21, v93, v95
	v_cvt_pk_bf16_f32 v22, v92, v94
	v_cvt_pk_bf16_f32 v23, v96, v97
	v_cvt_pk_bf16_f32 v24, v152, v153
	v_cvt_pk_bf16_f32 v25, v155, v157
	s_waitcnt lgkmcnt(3)
	v_mfma_f32_32x32x16_bf16 v[50:65], v[2:5], v[18:21], v[50:65]
	s_waitcnt lgkmcnt(1)
	v_mfma_f32_32x32x16_bf16 v[34:49], v[10:13], v[18:21], v[34:49]
	v_mfma_f32_32x32x16_bf16 v[50:65], v[6:9], v[22:25], v[50:65]
	s_waitcnt lgkmcnt(0)
	v_mfma_f32_32x32x16_bf16 v[34:49], v[14:17], v[22:25], v[34:49]
	v_sub_f32_e32 v2, v199, v146
	v_exp_f32_e32 v2, v2
	v_add_f32_e32 v3, v85, v86
	v_add_f32_e32 v2, v2, v3
	v_rcp_f32_e32 v2, v2
	s_nop 4
	v_pk_mul_f32 v[4:5], v[2:3], v[50:51] op_sel_hi:[0,1]
	v_pk_mul_f32 v[6:7], v[2:3], v[52:53] op_sel_hi:[0,1]
	v_cvt_pk_bf16_f32 v4, v4, v5
	v_cvt_pk_bf16_f32 v5, v6, v7
	v_add_co_u32_e32 v6, vcc, s27, v162
	v_pk_mul_f32 v[8:9], v[2:3], v[56:57] op_sel_hi:[0,1]
	s_nop 0
	v_addc_co_u32_e32 v7, vcc, 0, v163, vcc
	global_store_dwordx2 v[6:7], v[4:5], off
	v_pk_mul_f32 v[4:5], v[2:3], v[54:55] op_sel_hi:[0,1]
	v_cvt_pk_bf16_f32 v4, v4, v5
	v_cvt_pk_bf16_f32 v5, v8, v9
	global_store_dwordx2 v[6:7], v[4:5], off offset:16
	v_pk_mul_f32 v[4:5], v[2:3], v[58:59] op_sel_hi:[0,1]
	v_pk_mul_f32 v[8:9], v[2:3], v[60:61] op_sel_hi:[0,1]
	v_cvt_pk_bf16_f32 v4, v4, v5
	v_cvt_pk_bf16_f32 v5, v8, v9
	global_store_dwordx2 v[6:7], v[4:5], off offset:32
	v_pk_mul_f32 v[4:5], v[2:3], v[62:63] op_sel_hi:[0,1]
	v_pk_mul_f32 v[8:9], v[2:3], v[64:65] op_sel_hi:[0,1]
	v_cvt_pk_bf16_f32 v4, v4, v5
	v_cvt_pk_bf16_f32 v5, v8, v9
	global_store_dwordx2 v[6:7], v[4:5], off offset:48
	v_pk_mul_f32 v[4:5], v[2:3], v[34:35] op_sel_hi:[0,1]
	v_pk_mul_f32 v[8:9], v[2:3], v[36:37] op_sel_hi:[0,1]
	v_cvt_pk_bf16_f32 v4, v4, v5
	v_cvt_pk_bf16_f32 v5, v8, v9
	global_store_dwordx2 v[6:7], v[4:5], off offset:64
	v_pk_mul_f32 v[4:5], v[2:3], v[38:39] op_sel_hi:[0,1]
	v_pk_mul_f32 v[8:9], v[2:3], v[40:41] op_sel_hi:[0,1]
	v_cvt_pk_bf16_f32 v4, v4, v5
	v_cvt_pk_bf16_f32 v5, v8, v9
	global_store_dwordx2 v[6:7], v[4:5], off offset:80
	v_pk_mul_f32 v[4:5], v[2:3], v[42:43] op_sel_hi:[0,1]
	v_pk_mul_f32 v[8:9], v[2:3], v[44:45] op_sel_hi:[0,1]
	v_cvt_pk_bf16_f32 v4, v4, v5
	v_cvt_pk_bf16_f32 v5, v8, v9
	global_store_dwordx2 v[6:7], v[4:5], off offset:96
	v_pk_mul_f32 v[4:5], v[2:3], v[46:47] op_sel_hi:[0,1]
	v_pk_mul_f32 v[2:3], v[2:3], v[48:49] op_sel_hi:[0,1]
	v_cvt_pk_bf16_f32 v4, v4, v5
	v_cvt_pk_bf16_f32 v5, v2, v3
	global_store_dwordx2 v[6:7], v[4:5], off offset:112
	s_and_saveexec_b64 s[6:7], s[4:5]
	v_mov_b32_e32 v2, s28
	ds_write_b32 v2, v195
	s_or_b64 exec, exec, s[6:7]
	s_waitcnt lgkmcnt(0)
	s_barrier
	v_mov_b32_e32 v2, s28
	ds_read_b32 v2, v2
	s_mov_b64 s[20:21], -1
	s_andn2_b64 vcc, exec, s[18:19]
	v_readfirstlane_b32 s6, v0
	s_waitcnt lgkmcnt(0)
	v_readfirstlane_b32 s30, v2
	s_cbranch_vccnz .LBB0_1395
	s_and_saveexec_b64 s[6:7], s[4:5]
	s_cbranch_execz .LBB0_1483
	s_mov_b64 s[10:11], exec
	v_mbcnt_lo_u32_b32 v2, s10, 0
	v_mbcnt_hi_u32_b32 v2, s11, v2
	v_cmp_eq_u32_e32 vcc, 0, v2
	s_and_saveexec_b64 s[8:9], vcc
	s_cbranch_execz .LBB0_1482
	s_bcnt1_i32_b64 s10, s[10:11]
	v_mov_b32_e32 v3, s10
	global_atomic_add v3, v171, v3, s[12:13] sc0

; #define LAS __attribute__((address_space(3)))
; __device__ __forceinline__ unsigned pk2(float lo, float hi) { f32x2_t v = {lo, hi}; bf16x2_t b = __builtin_convertvector(v, bf16x2_t); return __builtin_bit_cast(unsigned, b); }
; __device__ __forceinline__ float fast_rcp(float x) { return __builtin_amdgcn_rcpf(x); }
; __device__ __forceinline__ void swa_p_compute(SwaRegs& R, const Args& a, Frame& F, int u) {
;     ...
;         for (int kb = 0; kb < 6; ++kb) if (kb >= kb0) {
;             v2u vlo[2][2], vhi[2][2];
; #pragma unroll
;             for (int s2 = 0; s2 < 2; ++s2)
; #pragma unroll
;                 for (int db = 0; db < 2; ++db) {
;                     const LAS unsigned char* vp = Vl + (db * 32 + r32) * SWA_VLD_B + (kb * 32 + s2 * 16 + 4 * hi) * 2;
;                     vlo[s2][db] = *(const LAS v2u*)vp; vhi[s2][db] = *(const LAS v2u*)(vp + 16);
;                 }
;             bf16x8 pb[2];
; #pragma unroll
;             for (int s2 = 0; s2 < 2; ++s2) {
;                 v4u pw; pw.x = pk2(sacc[kb][8 * s2 + 0], sacc[kb][8 * s2 + 1]); pw.y = pk2(sacc[kb][8 * s2 + 2], sacc[kb][8 * s2 + 3]);
;                 pw.z = pk2(sacc[kb][8 * s2 + 4], sacc[kb][8 * s2 + 5]); pw.w = pk2(sacc[kb][8 * s2 + 6], sacc[kb][8 * s2 + 7]);
;                 pb[s2] = __builtin_bit_cast(bf16x8, pw);
;             }
;             asm volatile("s_waitcnt lgkmcnt(0)" ::: "memory"); __builtin_amdgcn_sched_barrier(0);
; #pragma unroll
;             for (int s2 = 0; s2 < 2; ++s2)
; #pragma unroll
;                 for (int db = 0; db < 2; ++db) {
;                     v4u av; av.x = vlo[s2][db].x; av.y = vlo[s2][db].y; av.z = vhi[s2][db].x; av.w = vhi[s2][db].y;
;                     o[db] = __builtin_amdgcn_mfma_f32_32x32x16_bf16(__builtin_bit_cast(bf16x8, av), pb[s2], o[db], 0, 0, 0);
;                 }
;             __builtin_amdgcn_sched_barrier(0);
;         }
;         const float inv = fast_rcp(l);
; #pragma unroll
;         for (int db = 0; db < 2; ++db)
; #pragma unroll
;             for (int g4 = 0; g4 < 4; ++g4) {
;                 v2u w; w.x = pk2(o[db][4 * g4 + 0] * inv, o[db][4 * g4 + 1] * inv); w.y = pk2(o[db][4 * g4 + 2] * inv, o[db][4 * g4 + 3] * inv);
;                 *(v2u*)(qrow + db * 32 + 8 * g4 + 4 * hi) = w;
;             }
.LBB0_1525:
	v_sub_f32_e32 v162, v199, v162
	s_waitcnt lgkmcnt(0)
	v_add_f32_e32 v250, v163, v185
	v_mov_b32_e32 v185, v171
	v_exp_f32_e32 v183, v162
	v_lshl_add_u64 v[162:163], v[186:187], 0, v[184:185]
	ds_read2_b64 v[184:187], v198 offset0:160 offset1:162
	ds_read2_b64 v[230:233], v198 offset0:164 offset1:166
	ds_read2_b64 v[234:237], v197 offset0:192 offset1:194
	ds_read2_b64 v[238:241], v197 offset0:196 offset1:198
	s_waitcnt lgkmcnt(0)
	v_cvt_pk_bf16_f32 v242, v164, v165
	v_cvt_pk_bf16_f32 v243, v201, v204
	v_cvt_pk_bf16_f32 v244, v209, v214
	v_cvt_pk_bf16_f32 v245, v216, v219
	v_cvt_pk_bf16_f32 v246, v221, v223
	v_cvt_pk_bf16_f32 v247, v224, v225
	v_cvt_pk_bf16_f32 v248, v226, v227
	v_cvt_pk_bf16_f32 v249, v228, v229
	s_waitcnt lgkmcnt(3)
	v_mfma_f32_32x32x16_bf16 v[82:97], v[184:187], v[242:245], v[82:97]
	s_waitcnt lgkmcnt(1)
	v_mfma_f32_32x32x16_bf16 v[66:81], v[234:237], v[242:245], v[66:81]
	v_mfma_f32_32x32x16_bf16 v[82:97], v[230:233], v[246:249], v[82:97]
	s_waitcnt lgkmcnt(0)
	v_mfma_f32_32x32x16_bf16 v[66:81], v[238:241], v[246:249], v[66:81]
	ds_read2_b64 v[184:187], v198 offset0:168 offset1:170
	ds_read2_b64 v[224:227], v198 offset0:172 offset1:174
	ds_read2_b64 v[228:231], v197 offset0:200 offset1:202
	ds_read2_b64 v[232:235], v197 offset0:204 offset1:206
	s_waitcnt lgkmcnt(0)
	v_cvt_pk_bf16_f32 v200, v200, v202
	v_cvt_pk_bf16_f32 v201, v203, v205
	v_cvt_pk_bf16_f32 v202, v206, v207
	v_cvt_pk_bf16_f32 v203, v210, v212
	v_cvt_pk_bf16_f32 v204, v208, v211
	v_cvt_pk_bf16_f32 v205, v213, v215
	v_cvt_pk_bf16_f32 v206, v217, v218
	v_cvt_pk_bf16_f32 v207, v220, v222
	s_waitcnt lgkmcnt(3)
	v_mfma_f32_32x32x16_bf16 v[82:97], v[184:187], v[200:203], v[82:97]
	s_waitcnt lgkmcnt(1)
	v_mfma_f32_32x32x16_bf16 v[66:81], v[228:231], v[200:203], v[66:81]
	v_mfma_f32_32x32x16_bf16 v[82:97], v[224:227], v[204:207], v[82:97]
	s_waitcnt lgkmcnt(0)
	v_mfma_f32_32x32x16_bf16 v[66:81], v[232:235], v[204:207], v[66:81]
	v_add_f32_e32 v164, v183, v250
	v_rcp_f32_e32 v164, v164
	s_and_b64 vcc, exec, s[6:7]
	s_nop 8
	v_pk_mul_f32 v[66:67], v[164:165], v[66:67] op_sel_hi:[0,1]
	v_pk_mul_f32 v[68:69], v[164:165], v[68:69] op_sel_hi:[0,1]
	v_pk_mul_f32 v[82:83], v[164:165], v[82:83] op_sel_hi:[0,1]
	v_pk_mul_f32 v[84:85], v[164:165], v[84:85] op_sel_hi:[0,1]
	v_cvt_pk_bf16_f32 v66, v66, v67
	v_cvt_pk_bf16_f32 v67, v68, v69
	v_pk_mul_f32 v[86:87], v[164:165], v[86:87] op_sel_hi:[0,1]
	v_cvt_pk_bf16_f32 v82, v82, v83
	v_cvt_pk_bf16_f32 v83, v84, v85
	v_pk_mul_f32 v[84:85], v[164:165], v[88:89] op_sel_hi:[0,1]
	global_store_dwordx2 v[162:163], v[66:67], off offset:64
	v_pk_mul_f32 v[66:67], v[164:165], v[70:71] op_sel_hi:[0,1]
	v_pk_mul_f32 v[68:69], v[164:165], v[72:73] op_sel_hi:[0,1]
	global_store_dwordx2 v[162:163], v[82:83], off
	v_cvt_pk_bf16_f32 v82, v86, v87
	v_cvt_pk_bf16_f32 v83, v84, v85
	v_cvt_pk_bf16_f32 v66, v66, v67
	v_cvt_pk_bf16_f32 v67, v68, v69
	global_store_dwordx2 v[162:163], v[82:83], off offset:16
	v_pk_mul_f32 v[82:83], v[164:165], v[90:91] op_sel_hi:[0,1]
	v_pk_mul_f32 v[84:85], v[164:165], v[92:93] op_sel_hi:[0,1]
	global_store_dwordx2 v[162:163], v[66:67], off offset:80
	v_pk_mul_f32 v[66:67], v[164:165], v[74:75] op_sel_hi:[0,1]
	v_pk_mul_f32 v[68:69], v[164:165], v[76:77] op_sel_hi:[0,1]
	v_cvt_pk_bf16_f32 v82, v82, v83
	v_cvt_pk_bf16_f32 v83, v84, v85
	v_cvt_pk_bf16_f32 v66, v66, v67
	v_cvt_pk_bf16_f32 v67, v68, v69
	global_store_dwordx2 v[162:163], v[82:83], off offset:32
	v_pk_mul_f32 v[82:83], v[164:165], v[94:95] op_sel_hi:[0,1]
	v_pk_mul_f32 v[84:85], v[164:165], v[96:97] op_sel_hi:[0,1]
	global_store_dwordx2 v[162:163], v[66:67], off offset:96
	v_pk_mul_f32 v[66:67], v[164:165], v[78:79] op_sel_hi:[0,1]
	v_pk_mul_f32 v[68:69], v[164:165], v[80:81] op_sel_hi:[0,1]
	v_cvt_pk_bf16_f32 v82, v82, v83
	v_cvt_pk_bf16_f32 v83, v84, v85
	v_cvt_pk_bf16_f32 v66, v66, v67
	v_cvt_pk_bf16_f32 v67, v68, v69
	global_store_dwordx2 v[162:163], v[82:83], off offset:48
	global_store_dwordx2 v[162:163], v[66:67], off offset:112
	s_cbranch_vccz .LBB0_1535
	s_and_b64 vcc, exec, s[6:7]
	s_cbranch_vccz .LBB0_1536

; #define LAS __attribute__((address_space(3)))
; __device__ __forceinline__ void swa_p_compute(SwaRegs& R, const Args& a, Frame& F, int u) {
;     ...
;         for (int kb = 0; kb < 6; ++kb) {
;             if (kb >= kb0) {
;                 f32x16 c = {0.f, 0.f, 0.f, 0.f, 0.f, 0.f, 0.f, 0.f, 0.f, 0.f, 0.f, 0.f, 0.f, 0.f, 0.f, 0.f};
;                 bf16x8 kf[4];
; #pragma unroll
;                 for (int s = 0; s < 4; ++s) kf[s] = *(const LAS bf16x8*)(Kl + (kb * 32 + r32) * SWA_KLD_B + s * 32 + hi * 16);
; #pragma unroll
;                 for (int s = 0; s < 4; ++s) c = __builtin_amdgcn_mfma_f32_32x32x16_bf16(kf[s], qf[tb][s], c, 0, 0, 0);
;                 sacc[kb] = c;
;             }
.LBB0_1528:
	ds_read_b128 v[2:5], v175 offset:9216
	ds_read_b128 v[66:69], v175 offset:9248
	s_waitcnt vmcnt(9) lgkmcnt(1)
	v_mfma_f32_32x32x16_bf16 v[2:17], v[2:5], v[158:161], 0
	s_waitcnt lgkmcnt(0)
	v_mfma_f32_32x32x16_bf16 v[2:17], v[66:69], v[154:157], v[2:17]
	ds_read_b128 v[66:69], v175 offset:9280
	ds_read_b128 v[70:73], v175 offset:9312
	s_waitcnt lgkmcnt(1)
	v_mfma_f32_32x32x16_bf16 v[2:17], v[66:69], v[150:153], v[2:17]
	s_waitcnt vmcnt(8) lgkmcnt(0)
	v_mfma_f32_32x32x16_bf16 v[2:17], v[70:73], v[146:149], v[2:17]
	s_mov_b64 s[22:23], -1
	s_and_b64 vcc, exec, s[18:19]
	s_cbranch_vccnz .LBB0_1538

; #define LAS __attribute__((address_space(3)))
; __device__ __forceinline__ void swa_p_compute(SwaRegs& R, const Args& a, Frame& F, int u) {
;     ...
;         for (int kb = 0; kb < 6; ++kb) {
;             if (kb >= kb0) {
;                 f32x16 c = {0.f, 0.f, 0.f, 0.f, 0.f, 0.f, 0.f, 0.f, 0.f, 0.f, 0.f, 0.f, 0.f, 0.f, 0.f, 0.f};
;                 bf16x8 kf[4];
; #pragma unroll
;                 for (int s = 0; s < 4; ++s) kf[s] = *(const LAS bf16x8*)(Kl + (kb * 32 + r32) * SWA_KLD_B + s * 32 + hi * 16);
; #pragma unroll
;                 for (int s = 0; s < 4; ++s) c = __builtin_amdgcn_mfma_f32_32x32x16_bf16(kf[s], qf[tb][s], c, 0, 0, 0);
;                 sacc[kb] = c;
;             }
.LBB0_1531:
	ds_read_b128 v[50:53], v175 offset:18432
	ds_read_b128 v[54:57], v175 offset:18464
	s_and_b64 vcc, exec, s[6:7]
	s_waitcnt vmcnt(9) lgkmcnt(1)
	v_mfma_f32_32x32x16_bf16 v[82:97], v[50:53], v[158:161], 0
	s_waitcnt lgkmcnt(0)
	v_mfma_f32_32x32x16_bf16 v[82:97], v[54:57], v[154:157], v[82:97]
	ds_read_b128 v[50:53], v175 offset:18496
	ds_read_b128 v[54:57], v175 offset:18528
	s_waitcnt lgkmcnt(1)
	v_mfma_f32_32x32x16_bf16 v[82:97], v[50:53], v[150:153], v[82:97]
	ds_read_b128 v[50:53], v175 offset:23040
	ds_read_b128 v[184:187], v175 offset:23072
	s_waitcnt vmcnt(8) lgkmcnt(2)
	v_mfma_f32_32x32x16_bf16 v[82:97], v[54:57], v[146:149], v[82:97]
	s_waitcnt lgkmcnt(1)
	v_mfma_f32_32x32x16_bf16 v[50:65], v[50:53], v[158:161], 0
	s_waitcnt lgkmcnt(0)
	v_mfma_f32_32x32x16_bf16 v[50:65], v[184:187], v[154:157], v[50:65]
	ds_read_b128 v[154:157], v175 offset:23104
	ds_read_b128 v[158:161], v175 offset:23136
	s_waitcnt lgkmcnt(1)
	v_mfma_f32_32x32x16_bf16 v[50:65], v[154:157], v[150:153], v[50:65]
	v_mov_b32_e32 v150, v199
	s_waitcnt lgkmcnt(0)
	v_mfma_f32_32x32x16_bf16 v[50:65], v[158:161], v[146:149], v[50:65]
	s_cbranch_vccz .LBB0_1539
	s_and_b64 vcc, exec, s[6:7]
	s_cbranch_vccz .LBB0_1540

; #define LAS __attribute__((address_space(3)))
; __device__ __forceinline__ float fast_rcp(float x) { return __builtin_amdgcn_rcpf(x); }
; __device__ __forceinline__ void swa_p_compute(SwaRegs& R, const Args& a, Frame& F, int u) {
;     ...
;         for (int kb = 0; kb < 6; ++kb) if (kb >= kb0) {
;             v2u vlo[2][2], vhi[2][2];
; #pragma unroll
;             for (int s2 = 0; s2 < 2; ++s2)
; #pragma unroll
;                 for (int db = 0; db < 2; ++db) {
;                     const LAS unsigned char* vp = Vl + (db * 32 + r32) * SWA_VLD_B + (kb * 32 + s2 * 16 + 4 * hi) * 2;
;                     vlo[s2][db] = *(const LAS v2u*)vp; vhi[s2][db] = *(const LAS v2u*)(vp + 16);
;                 }
;             bf16x8 pb[2];
; #pragma unroll
;             for (int s2 = 0; s2 < 2; ++s2) {
;                 v4u pw; pw.x = pk2(sacc[kb][8 * s2 + 0], sacc[kb][8 * s2 + 1]); pw.y = pk2(sacc[kb][8 * s2 + 2], sacc[kb][8 * s2 + 3]);
;                 pw.z = pk2(sacc[kb][8 * s2 + 4], sacc[kb][8 * s2 + 5]); pw.w = pk2(sacc[kb][8 * s2 + 6], sacc[kb][8 * s2 + 7]);
;                 pb[s2] = __builtin_bit_cast(bf16x8, pw);
;             }
;             asm volatile("s_waitcnt lgkmcnt(0)" ::: "memory"); __builtin_amdgcn_sched_barrier(0);
; #pragma unroll
;             for (int s2 = 0; s2 < 2; ++s2)
; #pragma unroll
;                 for (int db = 0; db < 2; ++db) {
;                     v4u av; av.x = vlo[s2][db].x; av.y = vlo[s2][db].y; av.z = vhi[s2][db].x; av.w = vhi[s2][db].y;
;                     o[db] = __builtin_amdgcn_mfma_f32_32x32x16_bf16(__builtin_bit_cast(bf16x8, av), pb[s2], o[db], 0, 0, 0);
;                 }
;             __builtin_amdgcn_sched_barrier(0);
;         }
;         const float inv = fast_rcp(l);
; #pragma unroll
;         for (int db = 0; db < 2; ++db)
; #pragma unroll
;             for (int g4 = 0; g4 < 4; ++g4) {
;                 v2u w; w.x = pk2(o[db][4 * g4 + 0] * inv, o[db][4 * g4 + 1] * inv); w.y = pk2(o[db][4 * g4 + 2] * inv, o[db][4 * g4 + 3] * inv);
;                 *(v2u*)(qrow + db * 32 + 8 * g4 + 4 * hi) = w;
;             }
; template <int K> __device__ __forceinline__ void run_phase(const Args& args, LAS unsigned char* ldsp) {
;     ...
;             swa_p_compute(RB, args, F, u1);
;             if (F.tid == 0) qslot[3] = tn;
;             LDS_BAR();
;             u = u2; u1 = (int)qslot[3];
.LBB0_1559:
	ds_read2_b64 v[2:5], v198 offset0:160 offset1:162
	ds_read2_b64 v[6:9], v198 offset0:164 offset1:166
	ds_read2_b64 v[10:13], v197 offset0:192 offset1:194
	ds_read2_b64 v[14:17], v197 offset0:196 offset1:198
	s_waitcnt lgkmcnt(0)
	v_cvt_pk_bf16_f32 v18, v82, v83
	v_cvt_pk_bf16_f32 v19, v147, v148
	v_cvt_pk_bf16_f32 v20, v149, v150
	v_cvt_pk_bf16_f32 v21, v151, v154
	v_cvt_pk_bf16_f32 v22, v156, v158
	v_cvt_pk_bf16_f32 v23, v159, v160
	v_cvt_pk_bf16_f32 v24, v161, v164
	v_cvt_pk_bf16_f32 v25, v165, v184
	s_waitcnt lgkmcnt(3)
	v_mfma_f32_32x32x16_bf16 v[50:65], v[2:5], v[18:21], v[50:65]
	s_waitcnt lgkmcnt(1)
	v_mfma_f32_32x32x16_bf16 v[34:49], v[10:13], v[18:21], v[34:49]
	v_mfma_f32_32x32x16_bf16 v[50:65], v[6:9], v[22:25], v[50:65]
	s_waitcnt lgkmcnt(0)
	v_mfma_f32_32x32x16_bf16 v[34:49], v[14:17], v[22:25], v[34:49]
	ds_read2_b64 v[2:5], v198 offset0:168 offset1:170
	ds_read2_b64 v[6:9], v198 offset0:172 offset1:174
	ds_read2_b64 v[10:13], v197 offset0:200 offset1:202
	ds_read2_b64 v[14:17], v197 offset0:204 offset1:206
	s_waitcnt lgkmcnt(0)
	v_cvt_pk_bf16_f32 v18, v84, v87
	v_cvt_pk_bf16_f32 v19, v88, v89
	v_cvt_pk_bf16_f32 v20, v90, v91
	v_cvt_pk_bf16_f32 v21, v93, v95
	v_cvt_pk_bf16_f32 v22, v92, v94
	v_cvt_pk_bf16_f32 v23, v96, v97
	v_cvt_pk_bf16_f32 v24, v152, v153
	v_cvt_pk_bf16_f32 v25, v155, v157
	s_waitcnt lgkmcnt(3)
	v_mfma_f32_32x32x16_bf16 v[50:65], v[2:5], v[18:21], v[50:65]
	s_waitcnt lgkmcnt(1)
	v_mfma_f32_32x32x16_bf16 v[34:49], v[10:13], v[18:21], v[34:49]
	v_mfma_f32_32x32x16_bf16 v[50:65], v[6:9], v[22:25], v[50:65]
	s_waitcnt lgkmcnt(0)
	v_mfma_f32_32x32x16_bf16 v[34:49], v[14:17], v[22:25], v[34:49]
	v_sub_f32_e32 v2, v199, v146
	v_exp_f32_e32 v2, v2
	v_add_f32_e32 v3, v85, v86
	v_add_f32_e32 v2, v2, v3
	v_rcp_f32_e32 v2, v2
	s_nop 4
	v_pk_mul_f32 v[4:5], v[2:3], v[50:51] op_sel_hi:[0,1]
	v_pk_mul_f32 v[6:7], v[2:3], v[52:53] op_sel_hi:[0,1]
	v_cvt_pk_bf16_f32 v4, v4, v5
	v_cvt_pk_bf16_f32 v5, v6, v7
	v_add_co_u32_e32 v6, vcc, s27, v162
	v_pk_mul_f32 v[8:9], v[2:3], v[56:57] op_sel_hi:[0,1]
	s_nop 0
	v_addc_co_u32_e32 v7, vcc, 0, v163, vcc
	global_store_dwordx2 v[6:7], v[4:5], off
	v_pk_mul_f32 v[4:5], v[2:3], v[54:55] op_sel_hi:[0,1]
	v_cvt_pk_bf16_f32 v4, v4, v5
	v_cvt_pk_bf16_f32 v5, v8, v9
	global_store_dwordx2 v[6:7], v[4:5], off offset:16
	v_pk_mul_f32 v[4:5], v[2:3], v[58:59] op_sel_hi:[0,1]
	v_pk_mul_f32 v[8:9], v[2:3], v[60:61] op_sel_hi:[0,1]
	v_cvt_pk_bf16_f32 v4, v4, v5
	v_cvt_pk_bf16_f32 v5, v8, v9
	global_store_dwordx2 v[6:7], v[4:5], off offset:32
	v_pk_mul_f32 v[4:5], v[2:3], v[62:63] op_sel_hi:[0,1]
	v_pk_mul_f32 v[8:9], v[2:3], v[64:65] op_sel_hi:[0,1]
	v_cvt_pk_bf16_f32 v4, v4, v5
	v_cvt_pk_bf16_f32 v5, v8, v9
	global_store_dwordx2 v[6:7], v[4:5], off offset:48
	v_pk_mul_f32 v[4:5], v[2:3], v[34:35] op_sel_hi:[0,1]
	v_pk_mul_f32 v[8:9], v[2:3], v[36:37] op_sel_hi:[0,1]
	v_cvt_pk_bf16_f32 v4, v4, v5
	v_cvt_pk_bf16_f32 v5, v8, v9
	global_store_dwordx2 v[6:7], v[4:5], off offset:64
	v_pk_mul_f32 v[4:5], v[2:3], v[38:39] op_sel_hi:[0,1]
	v_pk_mul_f32 v[8:9], v[2:3], v[40:41] op_sel_hi:[0,1]
	v_cvt_pk_bf16_f32 v4, v4, v5
	v_cvt_pk_bf16_f32 v5, v8, v9
	global_store_dwordx2 v[6:7], v[4:5], off offset:80
	v_pk_mul_f32 v[4:5], v[2:3], v[42:43] op_sel_hi:[0,1]
	v_pk_mul_f32 v[8:9], v[2:3], v[44:45] op_sel_hi:[0,1]
	v_cvt_pk_bf16_f32 v4, v4, v5
	v_cvt_pk_bf16_f32 v5, v8, v9
	global_store_dwordx2 v[6:7], v[4:5], off offset:96
	v_pk_mul_f32 v[4:5], v[2:3], v[46:47] op_sel_hi:[0,1]
	v_pk_mul_f32 v[2:3], v[2:3], v[48:49] op_sel_hi:[0,1]
	v_cvt_pk_bf16_f32 v4, v4, v5
	v_cvt_pk_bf16_f32 v5, v2, v3
	global_store_dwordx2 v[6:7], v[4:5], off offset:112
	s_and_saveexec_b64 s[6:7], s[4:5]
	s_cbranch_execz .LBB0_1394
	v_mov_b32_e32 v2, s29
	ds_write_b32 v2, v195
	s_branch .LBB0_1394

; #define LAS __attribute__((address_space(3)))
; __global__ void __launch_bounds__(NWAVES * 64, 2) mk_fwd(Args args) {
;     extern __shared__ __attribute__((aligned(16))) unsigned char lds[];
;     LAS unsigned char* ldsp = (LAS unsigned char*)lds;
;     volatile LAS unsigned* MISC = (volatile LAS unsigned*)(ldsp + MISC_OFF);
;     if (threadIdx.x < 32) MISC[threadIdx.x] = 0u;
;     __syncthreads();
;     XcdBarrier bar = xcd_barrier_post((unsigned*)(args.ws + WS_CTL) + 4096, MISC + 8);
;     ...
;     MK_SEQ
;     ...
; }
	.amdhsa_kernel _Z6mk_fwd4Args
		.amdhsa_group_segment_fixed_size 0
		.amdhsa_private_segment_fixed_size 0
		.amdhsa_kernarg_size 448
		.amdhsa_user_sgpr_count 2
		.amdhsa_user_sgpr_dispatch_ptr 0
		.amdhsa_user_sgpr_queue_ptr 0
		.amdhsa_user_sgpr_kernarg_segment_ptr 1
		.amdhsa_user_sgpr_dispatch_id 0
		.amdhsa_user_sgpr_kernarg_preload_length 0
		.amdhsa_user_sgpr_kernarg_preload_offset 0
		.amdhsa_user_sgpr_private_segment_size 0
		.amdhsa_uses_dynamic_stack 0
		.amdhsa_enable_private_segment 0
		.amdhsa_system_sgpr_workgroup_id_x 1
		.amdhsa_system_sgpr_workgroup_id_y 0
		.amdhsa_system_sgpr_workgroup_id_z 0
		.amdhsa_system_sgpr_workgroup_info 0
		.amdhsa_system_vgpr_workitem_id 0
		.amdhsa_next_free_vgpr 256
		.amdhsa_next_free_sgpr 102
		.amdhsa_accum_offset 256
		.amdhsa_reserve_vcc 1
		.amdhsa_float_round_mode_32 0
		.amdhsa_float_round_mode_16_64 0
		.amdhsa_float_denorm_mode_32 3
		.amdhsa_float_denorm_mode_16_64 3
		.amdhsa_dx10_clamp 1
		.amdhsa_ieee_mode 1
		.amdhsa_fp16_overflow 0
		.amdhsa_tg_split 0
		.amdhsa_exception_fp_ieee_invalid_op 0
		.amdhsa_exception_fp_denorm_src 0
		.amdhsa_exception_fp_ieee_div_zero 0
		.amdhsa_exception_fp_ieee_overflow 0
		.amdhsa_exception_fp_ieee_underflow 0
		.amdhsa_exception_fp_ieee_inexact 0
		.amdhsa_exception_int_div_zero 0
	.end_amdhsa_kernel

; #define LAS __attribute__((address_space(3)))
; __global__ void __launch_bounds__(NWAVES * 64, 2) mk_fwd(Args args) {
;     extern __shared__ __attribute__((aligned(16))) unsigned char lds[];
;     LAS unsigned char* ldsp = (LAS unsigned char*)lds;
;     volatile LAS unsigned* MISC = (volatile LAS unsigned*)(ldsp + MISC_OFF);
;     if (threadIdx.x < 32) MISC[threadIdx.x] = 0u;
;     __syncthreads();
;     XcdBarrier bar = xcd_barrier_post((unsigned*)(args.ws + WS_CTL) + 4096, MISC + 8);
;     ...
;     MK_SEQ
;     ...
; }
amdhsa.kernels:
  - .agpr_count:     0
    .args:
      - .offset:         0
        .size:           192
        .value_kind:     by_value
      - .offset:         192
        .size:           4
        .value_kind:     hidden_block_count_x
      - .offset:         196
        .size:           4
        .value_kind:     hidden_block_count_y
      - .offset:         200
        .size:           4
        .value_kind:     hidden_block_count_z
      - .offset:         204
        .size:           2
        .value_kind:     hidden_group_size_x
      - .offset:         206
        .size:           2
        .value_kind:     hidden_group_size_y
      - .offset:         208
        .size:           2
        .value_kind:     hidden_group_size_z
      - .offset:         210
        .size:           2
        .value_kind:     hidden_remainder_x
      - .offset:         212
        .size:           2
        .value_kind:     hidden_remainder_y
      - .offset:         214
        .size:           2
        .value_kind:     hidden_remainder_z
      - .offset:         232
        .size:           8
        .value_kind:     hidden_global_offset_x
      - .offset:         240
        .size:           8
        .value_kind:     hidden_global_offset_y
      - .offset:         248
        .size:           8
        .value_kind:     hidden_global_offset_z
      - .offset:         256
        .size:           2
        .value_kind:     hidden_grid_dims
      - .offset:         312
        .size:           4
        .value_kind:     hidden_dynamic_lds_size
    .group_segment_fixed_size: 0
    .kernarg_segment_align: 8
    .kernarg_segment_size: 448
    .language:       OpenCL C
    .language_version:
      - 2
      - 0
    .max_flat_workgroup_size: 512
    .name:           _Z6mk_fwd4Args
    .private_segment_fixed_size: 0
    .sgpr_count:     108
    .sgpr_spill_count: 4
    .symbol:         _Z6mk_fwd4Args.kd
    .uniform_work_group_size: 1
    .uses_dynamic_stack: false
    .vgpr_count:     256
    .vgpr_spill_count: 0
    .wavefront_size: 64
